# phase 6/9 epilogues de-serialised (counted vmcnt, all residual loads in flight), x tile touch-prefetched during phase 6 K-loop
# speedup vs baseline: 1.0126x; 1.0126x over previous
; #define PG8_STAGE(bufoff, gbase, voff) do { _Pragma("unroll") for (int _i = 0; _i < 2; ++_i) \
;         __builtin_amdgcn_global_load_lds((const unsigned*)((const char*)(gbase) + (voff)[_i]), (LAS unsigned*)(lds + (bufoff) + ldsw + _i * 8192), 16, 0, 0); } while (0)
; #define PG8_WAIT_V(n) asm volatile("s_waitcnt vmcnt(" #n ")" ::: "memory")
; #define PG8_BAR __builtin_amdgcn_s_barrier()
; template <class Epi>
; DI void gemm_phase(LAS unsigned char* lds, const Gemm g, const StaticOrder& S, const Epi& E) {
;     ...
;     for (int i = 0; i < 2; ++i) { int R, C; stage_rc(tid * 16 + i * 8192, R, C); const int Rb = Epi::PERM ? ((R & ~31) + perm32(R & 31)) : R;
;         voffA[i] = (unsigned)(R * K + C) * 2u; voffB[i] = (unsigned)(Rb * K + C) * 2u; }
;     const size_t kstep = (size_t)(BK * 2);
;     const size_t hstep = (size_t)HALF * K * 2;
;     const size_t tstep = 2 * hstep;
;     const unsigned ldsw = (unsigned)wid * 1024u;
;     const int aoff = lds_byte(wr * 64 + fr, fq * 8), boff = lds_byte(wc * 32 + fr, fq * 8);
;     ...
;     Unit cur, nxt; int ui = 0;
;     if (!S.next(0, cur)) return;
;     f32x4 acc[2][2][4][2];
; #pragma unroll
;     for (int a = 0; a < 2; ++a)
; #pragma unroll
;         for (int b = 0; b < 2; ++b)
; #pragma unroll
;             for (int m = 0; m < 4; ++m)
; #pragma unroll
;                 for (int n = 0; n < 2; ++n) acc[a][b][m][n] = (f32x4){0.f, 0.f, 0.f, 0.f};
;     bf16x8 At[4][2], B0[2][2], B1[2][2];
;     const char* cA = (const char*)g.A + (size_t)cur.pm * tstep; const char* cB = (const char*)g.Bt + (size_t)cur.pn * tstep;
;     PG8_STAGE(PG8_SB(0, 0), cB, voffB); PG8_STAGE(PG8_SA(0, 0), cA, voffA); PG8_STAGE(PG8_SB(0, 1), cB + hstep, voffB); PG8_STAGE(PG8_SA(0, 1), cA + hstep, voffA);
;     if (wr == 1) PG8_BAR;
;     PG8_WAIT_V(4); PG8_BAR;
;     PG8_STAGE(PG8_SB(1, 0), cB + kstep, voffB); PG8_STAGE(PG8_SA(1, 0), cA + kstep, voffA); PG8_STAGE(PG8_SB(1, 1), cB + hstep + kstep, voffB);
;     PG8_WAIT_V(6); PG8_BAR;
.LBB0_716:
	s_add_u32 s8, s30, 0x3437a000
	s_addc_u32 s9, s31, 0
	s_add_u32 s63, s30, 0x1a92000
	s_addc_u32 s64, s31, 0
	s_lshl_b32 s12, s12, 5
	s_and_b32 s17, s12, 0x60
	s_mov_b64 s[12:13], 0x80
	s_add_i32 m0, s45, 0x18000
	v_lshl_add_u64 v[6:7], v[6:7], 0, s[12:13]
	s_lshl_b32 s16, s5, 13
	s_lshl_b32 s18, s17, 7
	s_waitcnt vmcnt(4)
	s_barrier
	global_load_lds_dwordx4 v[6:7], off
	v_lshl_add_u64 v[4:5], v[4:5], 0, s[12:13]
	s_add_i32 m0, s45, 0x1a000
	s_add_i32 s65, s45, 0x8000
	s_add_i32 s66, s45, 0xa000
	global_load_lds_dwordx4 v[4:5], off
	v_lshl_add_u64 v[2:3], v[2:3], 0, s[12:13]
	s_mov_b32 m0, s65
	s_add_u32 s14, s48, 0x40080
	global_load_lds_dwordx4 v[2:3], off
	v_lshl_add_u64 v[0:1], v[0:1], 0, s[12:13]
	s_mov_b32 m0, s66
	s_addc_u32 s15, s49, 0
	global_load_lds_dwordx4 v[0:1], off
	s_add_i32 m0, s45, 0x1c000
	v_lshl_add_u64 v[0:1], s[14:15], 0, v[146:147]
	global_load_lds_dwordx4 v[0:1], off
	v_lshl_add_u64 v[0:1], s[14:15], 0, v[150:151]
	s_add_i32 m0, s45, 0x1e000
	s_sext_i32_i8 s72, s4
	global_load_lds_dwordx4 v[0:1], off
	v_and_b32_e32 v0, 15, v180
	v_lshlrev_b32_e32 v1, 1, v11
	v_lshlrev_b32_e32 v2, 2, v180
	v_lshlrev_b32_e32 v3, 6, v180
	s_movk_i32 s4, 0x3c0
	v_lshl_or_b32 v162, s5, 6, v0
	v_lshl_or_b32 v0, v0, 6, v1
	v_and_b32_e32 v2, 32, v2
	v_and_or_b32 v1, v3, s4, v1
	v_bitop3_b32 v163, s18, v1, v2 bitop3:0xf6
	v_lshlrev_b32_e32 v1, 8, v180
	v_bitop3_b32 v0, v0, s16, v2 bitop3:0xde
	v_and_b32_e32 v1, 0x38000, v1
	v_lshlrev_b32_e32 v2, 11, v10
	v_or3_b32 v1, v8, v1, v2
	v_add_u32_e32 v152, v1, v9
	v_lshlrev_b32_e32 v1, 4, v12
	s_waitcnt vmcnt(6)
	v_and_b32_e32 v1, 0x78000, v1
	v_or3_b32 v1, v8, v1, v2
	s_add_i32 s70, 0, 0x10000
	s_add_i32 s71, 0, 0x14000
	s_waitcnt lgkmcnt(0)
	s_ashr_i32 s67, s3, 31
	v_or_b32_e32 v164, s17, v11
	v_mov_b32_e32 v153, v147
	v_add_u32_e32 v154, v1, v9
	v_mov_b32_e32 v155, v147
	v_mov_b64_e32 v[156:157], 0x400
	v_mov_b64_e32 v[158:159], 0x3ff
	v_add_u32_e32 v165, s70, v163
	v_add_u32_e32 v166, 0, v0
	v_add_u32_e32 v167, s71, v163
	s_mov_b64 s[14:15], 0x20000
	s_mov_b64 s[16:17], 0x24000
	s_mov_b64 s[18:19], 0x28000
	s_mov_b64 s[22:23], 0x2c000
	v_and_b32_e32 v249, 63, v180
	v_lshrrev_b32_e32 v248, 4, v249
	v_lshl_add_u32 v248, v181, 5, v248
	v_lshlrev_b32_e32 v248, 12, v248
	v_bfe_u32 v249, v249, 1, 3
	v_lshl_add_u32 v248, v249, 7, v248
	s_barrier

; #define PG8_STAGE(bufoff, gbase, voff) do { _Pragma("unroll") for (int _i = 0; _i < 2; ++_i) \
;         __builtin_amdgcn_global_load_lds((const unsigned*)((const char*)(gbase) + (voff)[_i]), (LAS unsigned*)(lds + (bufoff) + ldsw + _i * 8192), 16, 0, 0); } while (0)
; #define PG8_LDA(dst, b, h) do { _Pragma("unroll") for (int m = 0; m < 4; ++m) _Pragma("unroll") for (int k = 0; k < 2; ++k) dst[m][k] = *(const LAS bf16x8*)(lds + PG8_SA(b, h) + aoff + m * 2048 + k * 1024); } while (0)
; #define PG8_LDB(dst, b, h) do { _Pragma("unroll") for (int n = 0; n < 2; ++n) _Pragma("unroll") for (int k = 0; k < 2; ++k) dst[n][k] = *(const LAS bf16x8*)(lds + PG8_SB(b, h) + boff + n * 2048 + k * 1024); } while (0)
; #define PG8_MMA(ai, bj, At, Bt) do { __builtin_amdgcn_s_setprio(1); _Pragma("unroll") for (int m = 0; m < 4; ++m) _Pragma("unroll") for (int n = 0; n < 2; ++n) _Pragma("unroll") for (int k = 0; k < 2; ++k) \
;         acc[ai][bj][m][n] = __builtin_amdgcn_mfma_f32_16x16x32_bf16(Bt[n][k], At[m][k], acc[ai][bj][m][n], 0, 0, 0); __builtin_amdgcn_s_setprio(0); } while (0)
; #define PG8_WAIT_L(n) asm volatile("s_waitcnt lgkmcnt(" #n ")" ::: "memory")
; #define PG8_BAR __builtin_amdgcn_s_barrier()
; #define PG8_SCHED __builtin_amdgcn_sched_barrier(0)
; template <class Epi>
; DI void gemm_phase(LAS unsigned char* lds, const Gemm g, const StaticOrder& S, const Epi& E) {
;     ...
;             PG8_LDB(B0, 0, 0); PG8_SCHED; PG8_LDA(At, 0, 0); PG8_STAGE(PG8_SA(1, 1), a1 + hstep, voffA);
;             PG8_WAIT_L(8); PG8_BAR; PG8_WAIT_L(0); PG8_MMA(0, 0, At, B0); PG8_BAR; PG8_SCHED;
;             PG8_LDB(B1, 0, 1); PG8_STAGE(PG8_SB(0, 0), b2, voffB);
;             PG8_BAR; PG8_WAIT_L(0); PG8_MMA(0, 1, At, B1); PG8_BAR;
;             PG8_LDA(At, 0, 1); PG8_STAGE(PG8_SA(0, 0), a2, voffA);
;             PG8_BAR; PG8_WAIT_L(0); PG8_MMA(1, 0, At, B0); PG8_BAR; PG8_SCHED;
.LBB0_724:
	ds_read_b128 v[128:131], v165
	ds_read_b128 v[132:135], v165 offset:1024
	ds_read_b128 v[136:139], v165 offset:2048
	ds_read_b128 v[140:143], v165 offset:3072
	s_add_u32 s48, s46, 0xfffc0080
	s_addc_u32 s49, s47, -1
	s_cmp_eq_u32 s77, 12
	s_cselect_b32 s51, s39, s49
	s_cselect_b32 s50, s73, s48
	s_cselect_b32 s49, s25, s76
	s_cselect_b32 s48, s74, s75
	v_lshl_add_u64 v[160:161], s[46:47], 0, v[152:153]
	s_add_i32 m0, s45, 0xc000
	ds_read_b128 v[168:171], v166
	ds_read_b128 v[172:175], v166 offset:1024
	ds_read_b128 v[176:179], v166 offset:2048
	ds_read_b128 v[182:185], v166 offset:3072
	ds_read_b128 v[186:189], v166 offset:4096
	ds_read_b128 v[190:193], v166 offset:5120
	ds_read_b128 v[194:197], v166 offset:6144
	ds_read_b128 v[198:201], v166 offset:7168
	global_load_lds_dwordx4 v[160:161], off
	v_lshl_add_u64 v[160:161], s[46:47], 0, v[154:155]
	s_add_i32 m0, s45, 0xe000
	s_nop 0
	global_load_lds_dwordx4 v[160:161], off
	s_waitcnt lgkmcnt(8)
	s_barrier
	s_waitcnt lgkmcnt(0)
	s_setprio 1
	s_waitcnt lgkmcnt(0)
	v_mfma_f32_16x16x32_bf16 v[124:127], v[128:131], v[168:171], v[124:127]
	v_mfma_f32_16x16x32_bf16 v[120:123], v[136:139], v[168:171], v[120:123]
	v_mfma_f32_16x16x32_bf16 v[108:111], v[128:131], v[176:179], v[108:111]
	v_mfma_f32_16x16x32_bf16 v[104:107], v[136:139], v[176:179], v[104:107]
	v_mfma_f32_16x16x32_bf16 v[92:95], v[128:131], v[186:189], v[92:95]
	v_mfma_f32_16x16x32_bf16 v[88:91], v[136:139], v[186:189], v[88:91]
	v_mfma_f32_16x16x32_bf16 v[76:79], v[128:131], v[194:197], v[76:79]
	v_mfma_f32_16x16x32_bf16 v[72:75], v[136:139], v[194:197], v[72:75]
	v_mfma_f32_16x16x32_bf16 v[124:127], v[132:135], v[172:175], v[124:127]
	v_mfma_f32_16x16x32_bf16 v[120:123], v[140:143], v[172:175], v[120:123]
	v_mfma_f32_16x16x32_bf16 v[108:111], v[132:135], v[182:185], v[108:111]
	v_mfma_f32_16x16x32_bf16 v[104:107], v[140:143], v[182:185], v[104:107]
	v_mfma_f32_16x16x32_bf16 v[92:95], v[132:135], v[190:193], v[92:95]
	v_mfma_f32_16x16x32_bf16 v[88:91], v[140:143], v[190:193], v[88:91]
	v_mfma_f32_16x16x32_bf16 v[76:79], v[132:135], v[198:201], v[76:79]
	v_mfma_f32_16x16x32_bf16 v[72:75], v[140:143], v[198:201], v[72:75]
	s_setprio 0
	s_barrier
	s_add_i32 s78, s70, s58
	v_lshl_add_u64 v[160:161], s[48:49], 0, v[146:147]
	s_mov_b32 m0, s78
	ds_read_b128 v[202:205], v167
	ds_read_b128 v[206:209], v167 offset:1024
	ds_read_b128 v[210:213], v167 offset:2048
	ds_read_b128 v[214:217], v167 offset:3072
	global_load_lds_dwordx4 v[160:161], off
	v_lshl_add_u64 v[218:219], s[48:49], 0, v[150:151]
	s_add_i32 m0, s78, 0x2000
	s_nop 0
	global_load_lds_dwordx4 v[218:219], off
	s_barrier
	s_waitcnt lgkmcnt(0)
	s_setprio 1
	s_waitcnt lgkmcnt(0)
	v_mfma_f32_16x16x32_bf16 v[116:119], v[202:205], v[168:171], v[116:119]
	v_mfma_f32_16x16x32_bf16 v[112:115], v[210:213], v[168:171], v[112:115]
	v_mfma_f32_16x16x32_bf16 v[100:103], v[202:205], v[176:179], v[100:103]
	v_mfma_f32_16x16x32_bf16 v[96:99], v[210:213], v[176:179], v[96:99]
	v_mfma_f32_16x16x32_bf16 v[84:87], v[202:205], v[186:189], v[84:87]
	v_mfma_f32_16x16x32_bf16 v[80:83], v[210:213], v[186:189], v[80:83]
	v_mfma_f32_16x16x32_bf16 v[68:71], v[202:205], v[194:197], v[68:71]
	v_mfma_f32_16x16x32_bf16 v[64:67], v[210:213], v[194:197], v[64:67]
	v_mfma_f32_16x16x32_bf16 v[116:119], v[206:209], v[172:175], v[116:119]
	v_mfma_f32_16x16x32_bf16 v[112:115], v[214:217], v[172:175], v[112:115]
	v_mfma_f32_16x16x32_bf16 v[100:103], v[206:209], v[182:185], v[100:103]
	v_mfma_f32_16x16x32_bf16 v[96:99], v[214:217], v[182:185], v[96:99]
	v_mfma_f32_16x16x32_bf16 v[84:87], v[206:209], v[190:193], v[84:87]
	v_mfma_f32_16x16x32_bf16 v[80:83], v[214:217], v[190:193], v[80:83]
	v_mfma_f32_16x16x32_bf16 v[68:71], v[206:209], v[198:201], v[68:71]
	v_mfma_f32_16x16x32_bf16 v[64:67], v[214:217], v[198:201], v[64:67]
	s_setprio 0
	s_mov_b32 m0, s45
	v_lshl_add_u64 v[220:221], s[50:51], 0, v[144:145]
	s_barrier
	ds_read_b128 v[168:171], v166 offset:16384
	ds_read_b128 v[172:175], v166 offset:17408
	ds_read_b128 v[176:179], v166 offset:18432
	ds_read_b128 v[182:185], v166 offset:19456
	ds_read_b128 v[186:189], v166 offset:20480
	ds_read_b128 v[190:193], v166 offset:21504
	ds_read_b128 v[194:197], v166 offset:22528
	ds_read_b128 v[198:201], v166 offset:23552
	global_load_lds_dwordx4 v[220:221], off
	v_lshl_add_u64 v[222:223], s[50:51], 0, v[148:149]
	s_mov_b32 m0, s59
	s_nop 0
	global_load_lds_dwordx4 v[222:223], off
	s_barrier
	s_waitcnt lgkmcnt(0)
	s_setprio 1
	s_waitcnt lgkmcnt(0)
	v_mfma_f32_16x16x32_bf16 v[60:63], v[128:131], v[168:171], v[60:63]
	v_mfma_f32_16x16x32_bf16 v[56:59], v[136:139], v[168:171], v[56:59]
	v_mfma_f32_16x16x32_bf16 v[44:47], v[128:131], v[176:179], v[44:47]
	v_mfma_f32_16x16x32_bf16 v[40:43], v[136:139], v[176:179], v[40:43]
	v_mfma_f32_16x16x32_bf16 v[28:31], v[128:131], v[186:189], v[28:31]
	v_mfma_f32_16x16x32_bf16 v[24:27], v[136:139], v[186:189], v[24:27]
	v_mfma_f32_16x16x32_bf16 v[12:15], v[128:131], v[194:197], v[12:15]
	v_mfma_f32_16x16x32_bf16 v[8:11], v[136:139], v[194:197], v[8:11]
	v_mfma_f32_16x16x32_bf16 v[60:63], v[132:135], v[172:175], v[60:63]
	v_mfma_f32_16x16x32_bf16 v[56:59], v[140:143], v[172:175], v[56:59]
	v_mfma_f32_16x16x32_bf16 v[44:47], v[132:135], v[182:185], v[44:47]
	v_mfma_f32_16x16x32_bf16 v[40:43], v[140:143], v[182:185], v[40:43]
	v_mfma_f32_16x16x32_bf16 v[28:31], v[132:135], v[190:193], v[28:31]
	v_mfma_f32_16x16x32_bf16 v[24:27], v[140:143], v[190:193], v[24:27]
	v_mfma_f32_16x16x32_bf16 v[12:15], v[132:135], v[198:201], v[12:15]
	v_mfma_f32_16x16x32_bf16 v[8:11], v[140:143], v[198:201], v[8:11]
	s_setprio 0
	s_barrier
; #define PG8_STAGE(bufoff, gbase, voff) do { _Pragma("unroll") for (int _i = 0; _i < 2; ++_i) \
;         __builtin_amdgcn_global_load_lds((const unsigned*)((const char*)(gbase) + (voff)[_i]), (LAS unsigned*)(lds + (bufoff) + ldsw + _i * 8192), 16, 0, 0); } while (0)
; #define PG8_LDA(dst, b, h) do { _Pragma("unroll") for (int m = 0; m < 4; ++m) _Pragma("unroll") for (int k = 0; k < 2; ++k) dst[m][k] = *(const LAS bf16x8*)(lds + PG8_SA(b, h) + aoff + m * 2048 + k * 1024); } while (0)
; #define PG8_LDB(dst, b, h) do { _Pragma("unroll") for (int n = 0; n < 2; ++n) _Pragma("unroll") for (int k = 0; k < 2; ++k) dst[n][k] = *(const LAS bf16x8*)(lds + PG8_SB(b, h) + boff + n * 2048 + k * 1024); } while (0)
; #define PG8_MMA(ai, bj, At, Bt) do { __builtin_amdgcn_s_setprio(1); _Pragma("unroll") for (int m = 0; m < 4; ++m) _Pragma("unroll") for (int n = 0; n < 2; ++n) _Pragma("unroll") for (int k = 0; k < 2; ++k) \
;         acc[ai][bj][m][n] = __builtin_amdgcn_mfma_f32_16x16x32_bf16(Bt[n][k], At[m][k], acc[ai][bj][m][n], 0, 0, 0); __builtin_amdgcn_s_setprio(0); } while (0)
; #define PG8_WAIT_V(n) asm volatile("s_waitcnt vmcnt(" #n ")" ::: "memory")
; #define PG8_WAIT_L(n) asm volatile("s_waitcnt lgkmcnt(" #n ")" ::: "memory")
; #define PG8_BAR __builtin_amdgcn_s_barrier()
; #define PG8_SCHED __builtin_amdgcn_sched_barrier(0)
; template <class Epi>
; DI void gemm_phase(LAS unsigned char* lds, const Gemm g, const StaticOrder& S, const Epi& E) {
;     ...
;             PG8_STAGE(PG8_SB(0, 1), b2 + hstep, voffB);
;             PG8_WAIT_V(6); PG8_BAR; PG8_MMA(1, 1, At, B1); PG8_BAR;
;             PG8_LDB(B0, 1, 0); PG8_SCHED; PG8_LDA(At, 1, 0); PG8_STAGE(PG8_SA(0, 1), a2 + hstep, voffA);
;             PG8_WAIT_L(8); PG8_BAR; PG8_WAIT_L(0); PG8_MMA(0, 0, At, B0); PG8_BAR; PG8_SCHED;
;             PG8_LDB(B1, 1, 1); PG8_STAGE(PG8_SB(1, 0), b3, voffB);
;             PG8_BAR; PG8_WAIT_L(0); PG8_MMA(0, 1, At, B1); PG8_BAR;
	s_add_u32 s78, s48, 0x40000
	s_addc_u32 s79, s49, 0
	s_add_i32 s80, s71, s58
	v_lshl_add_u64 v[128:129], s[78:79], 0, v[146:147]
	s_mov_b32 m0, s80
	s_nop 0
	global_load_lds_dwordx4 v[128:129], off
	v_lshl_add_u64 v[128:129], s[78:79], 0, v[150:151]
	s_add_i32 m0, s80, 0x2000
	s_nop 0
	global_load_lds_dwordx4 v[128:129], off
	s_lshl_b32 s84, s44, 20
	s_lshl_b32 s85, s72, 10
	s_add_u32 s84, s84, s85
	s_add_i32 s85, s77, 2
	s_lshl_b32 s85, s85, 13
	s_add_u32 s84, s84, s85
	s_add_u32 s84, s36, s84
	s_addc_u32 s85, s37, 0
	s_waitcnt vmcnt(6)
	global_load_dword v249, v248, s[84:85]
	s_barrier
	s_setprio 1
	v_mfma_f32_16x16x32_bf16 v[52:55], v[202:205], v[168:171], v[52:55]
	v_mfma_f32_16x16x32_bf16 v[48:51], v[210:213], v[168:171], v[48:51]
	v_mfma_f32_16x16x32_bf16 v[36:39], v[202:205], v[176:179], v[36:39]
	v_mfma_f32_16x16x32_bf16 v[32:35], v[210:213], v[176:179], v[32:35]
	v_mfma_f32_16x16x32_bf16 v[20:23], v[202:205], v[186:189], v[20:23]
	v_mfma_f32_16x16x32_bf16 v[16:19], v[210:213], v[186:189], v[16:19]
	v_mfma_f32_16x16x32_bf16 v[4:7], v[202:205], v[194:197], v[4:7]
	v_mfma_f32_16x16x32_bf16 v[0:3], v[210:213], v[194:197], v[0:3]
	v_mfma_f32_16x16x32_bf16 v[52:55], v[206:209], v[172:175], v[52:55]
	v_mfma_f32_16x16x32_bf16 v[48:51], v[214:217], v[172:175], v[48:51]
	v_mfma_f32_16x16x32_bf16 v[36:39], v[206:209], v[182:185], v[36:39]
	v_mfma_f32_16x16x32_bf16 v[32:35], v[214:217], v[182:185], v[32:35]
	v_mfma_f32_16x16x32_bf16 v[20:23], v[206:209], v[190:193], v[20:23]
	v_mfma_f32_16x16x32_bf16 v[16:19], v[214:217], v[190:193], v[16:19]
	v_mfma_f32_16x16x32_bf16 v[4:7], v[206:209], v[198:201], v[4:7]
	v_mfma_f32_16x16x32_bf16 v[0:3], v[214:217], v[198:201], v[0:3]
	s_setprio 0
	s_add_i32 s78, 0, 0x18000
	v_add_u32_e32 v140, s78, v163
	s_barrier
	ds_read_b128 v[128:131], v140
	ds_read_b128 v[132:135], v140 offset:1024
	ds_read_b128 v[136:139], v140 offset:2048
	ds_read_b128 v[140:143], v140 offset:3072
	s_add_u32 s50, s50, 0x40000
	s_addc_u32 s51, s51, 0
	s_mov_b32 m0, s60
	v_lshl_add_u64 v[202:203], s[50:51], 0, v[144:145]
	ds_read_b128 v[168:171], v166 offset:32768
	ds_read_b128 v[172:175], v166 offset:33792
	ds_read_b128 v[176:179], v166 offset:34816
	ds_read_b128 v[182:185], v166 offset:35840
	ds_read_b128 v[186:189], v166 offset:36864
	ds_read_b128 v[190:193], v166 offset:37888
	ds_read_b128 v[194:197], v166 offset:38912
	ds_read_b128 v[198:201], v166 offset:39936
	global_load_lds_dwordx4 v[202:203], off
	v_lshl_add_u64 v[202:203], s[50:51], 0, v[148:149]
	s_mov_b32 m0, s61
	s_nop 0
	global_load_lds_dwordx4 v[202:203], off
	s_waitcnt lgkmcnt(8)
	s_barrier
	s_waitcnt lgkmcnt(0)
	s_setprio 1
	s_waitcnt lgkmcnt(0)
	v_mfma_f32_16x16x32_bf16 v[124:127], v[128:131], v[168:171], v[124:127]
	v_mfma_f32_16x16x32_bf16 v[120:123], v[136:139], v[168:171], v[120:123]
	v_mfma_f32_16x16x32_bf16 v[108:111], v[128:131], v[176:179], v[108:111]
	v_mfma_f32_16x16x32_bf16 v[104:107], v[136:139], v[176:179], v[104:107]
	v_mfma_f32_16x16x32_bf16 v[92:95], v[128:131], v[186:189], v[92:95]
	v_mfma_f32_16x16x32_bf16 v[88:91], v[136:139], v[186:189], v[88:91]
	v_mfma_f32_16x16x32_bf16 v[76:79], v[128:131], v[194:197], v[76:79]
	v_mfma_f32_16x16x32_bf16 v[72:75], v[136:139], v[194:197], v[72:75]
	v_mfma_f32_16x16x32_bf16 v[124:127], v[132:135], v[172:175], v[124:127]
	v_mfma_f32_16x16x32_bf16 v[120:123], v[140:143], v[172:175], v[120:123]
	v_mfma_f32_16x16x32_bf16 v[108:111], v[132:135], v[182:185], v[108:111]
	v_mfma_f32_16x16x32_bf16 v[104:107], v[140:143], v[182:185], v[104:107]
	v_mfma_f32_16x16x32_bf16 v[92:95], v[132:135], v[190:193], v[92:95]
	v_mfma_f32_16x16x32_bf16 v[88:91], v[140:143], v[190:193], v[88:91]
	v_mfma_f32_16x16x32_bf16 v[76:79], v[132:135], v[198:201], v[76:79]
	v_mfma_f32_16x16x32_bf16 v[72:75], v[140:143], v[198:201], v[72:75]
	s_setprio 0
	s_barrier
	s_add_i32 s50, 0, 0x1c000
	s_add_i32 s51, s78, s58
	v_add_u32_e32 v214, s50, v163
	v_lshl_add_u64 v[160:161], v[160:161], 0, s[12:13]
	s_mov_b32 m0, s51
	ds_read_b128 v[202:205], v214
	ds_read_b128 v[206:209], v214 offset:1024
	ds_read_b128 v[210:213], v214 offset:2048
	ds_read_b128 v[214:217], v214 offset:3072
	global_load_lds_dwordx4 v[160:161], off
	v_lshl_add_u64 v[160:161], v[218:219], 0, s[12:13]
	s_add_i32 m0, s51, 0x2000
	s_nop 0
	global_load_lds_dwordx4 v[160:161], off
	s_barrier
	s_waitcnt lgkmcnt(0)
	s_setprio 1
	s_waitcnt lgkmcnt(0)
	v_mfma_f32_16x16x32_bf16 v[116:119], v[202:205], v[168:171], v[116:119]
	v_mfma_f32_16x16x32_bf16 v[112:115], v[210:213], v[168:171], v[112:115]
	v_mfma_f32_16x16x32_bf16 v[100:103], v[202:205], v[176:179], v[100:103]
	v_mfma_f32_16x16x32_bf16 v[96:99], v[210:213], v[176:179], v[96:99]
	v_mfma_f32_16x16x32_bf16 v[84:87], v[202:205], v[186:189], v[84:87]
	v_mfma_f32_16x16x32_bf16 v[80:83], v[210:213], v[186:189], v[80:83]
	v_mfma_f32_16x16x32_bf16 v[68:71], v[202:205], v[194:197], v[68:71]
	v_mfma_f32_16x16x32_bf16 v[64:67], v[210:213], v[194:197], v[64:67]
	v_mfma_f32_16x16x32_bf16 v[116:119], v[206:209], v[172:175], v[116:119]
	v_mfma_f32_16x16x32_bf16 v[112:115], v[214:217], v[172:175], v[112:115]
	v_mfma_f32_16x16x32_bf16 v[100:103], v[206:209], v[182:185], v[100:103]
	v_mfma_f32_16x16x32_bf16 v[96:99], v[214:217], v[182:185], v[96:99]
	v_mfma_f32_16x16x32_bf16 v[84:87], v[206:209], v[190:193], v[84:87]
	v_mfma_f32_16x16x32_bf16 v[80:83], v[214:217], v[190:193], v[80:83]
	v_mfma_f32_16x16x32_bf16 v[68:71], v[206:209], v[198:201], v[68:71]
	v_mfma_f32_16x16x32_bf16 v[64:67], v[214:217], v[198:201], v[64:67]
	s_setprio 0
	s_mov_b32 m0, s65
	v_lshl_add_u64 v[160:161], v[220:221], 0, s[12:13]
	s_barrier
; DI unsigned pk2(float a, float b) { f32x2 v = {a, b}; bf16x2_t r = __builtin_convertvector(v, bf16x2_t); return __builtin_bit_cast(unsigned, r); }
; #define PG8_STAGE(bufoff, gbase, voff) do { _Pragma("unroll") for (int _i = 0; _i < 2; ++_i) \
;         __builtin_amdgcn_global_load_lds((const unsigned*)((const char*)(gbase) + (voff)[_i]), (LAS unsigned*)(lds + (bufoff) + ldsw + _i * 8192), 16, 0, 0); } while (0)
; #define PG8_LDA(dst, b, h) do { _Pragma("unroll") for (int m = 0; m < 4; ++m) _Pragma("unroll") for (int k = 0; k < 2; ++k) dst[m][k] = *(const LAS bf16x8*)(lds + PG8_SA(b, h) + aoff + m * 2048 + k * 1024); } while (0)
; #define PG8_WAIT_V(n) asm volatile("s_waitcnt vmcnt(" #n ")" ::: "memory")
; #define PG8_WAIT_L(n) asm volatile("s_waitcnt lgkmcnt(" #n ")" ::: "memory")
; #define PG8_BAR __builtin_amdgcn_s_barrier()
; template <class Epi>
; DI void gemm_phase(LAS unsigned char* lds, const Gemm g, const StaticOrder& S, const Epi& E) {
;     ...
;             PG8_LDA(At, 1, 1); PG8_STAGE(PG8_SA(1, 0), a3, voffA);
;             PG8_BAR; PG8_WAIT_L(0); PG8_MMA(1, 0, At, B0); PG8_BAR; PG8_SCHED;
;             PG8_STAGE(PG8_SB(1, 1), b3 + hstep, voffB);
;             PG8_WAIT_V(6); PG8_BAR; PG8_MMA(1, 1, At, B1); PG8_BAR;
;     DI void operator()(const f32x4 (&acc)[2][2][4][2], const Unit& u, int wr, int wc, int fr, int fq) const {
;         const int row0 = u.pm * BM + wr * 64 + fr, col0 = u.pn * BM + wc * 32 + 8 * fq;
;         const float* gp = gate + (size_t)((u.pm * BM) >> 12) * NMODC + col0;
;         f32x4 gv[2][2];
; #pragma unroll
;         for (int bj = 0; bj < 2; ++bj)
; #pragma unroll
;             for (int n = 0; n < 2; ++n) gv[bj][n] = *(const f32x4*)(gp + bj * HALF + n * 4);
; #pragma unroll
;         for (int ai = 0; ai < 2; ++ai)
; #pragma unroll
;             for (int m = 0; m < 4; ++m) { const size_t ro = (size_t)(row0 + ai * HALF + m * 16) * DM + col0;
; #pragma unroll
;                 for (int bj = 0; bj < 2; ++bj) {
;                     const f32x4 x0 = *(const f32x4*)(base + ro + bj * HALF) + gv[bj][0] * acc[ai][bj][m][0], x1 = *(const f32x4*)(base + ro + bj * HALF + 4) + gv[bj][1] * acc[ai][bj][m][1];
;                     u32x4 w; w.x = pk2(x0.x, x0.y); w.y = pk2(x0.z, x0.w); w.z = pk2(x1.x, x1.y); w.w = pk2(x1.z, x1.w);
;                     *(u32x4*)(outb + ro + bj * HALF) = w; } }
	ds_read_b128 v[168:171], v166 offset:49152
	ds_read_b128 v[172:175], v166 offset:50176
	ds_read_b128 v[176:179], v166 offset:51200
	ds_read_b128 v[182:185], v166 offset:52224
	ds_read_b128 v[186:189], v166 offset:53248
	ds_read_b128 v[190:193], v166 offset:54272
	ds_read_b128 v[194:197], v166 offset:55296
	ds_read_b128 v[198:201], v166 offset:56320
	global_load_lds_dwordx4 v[160:161], off
	v_lshl_add_u64 v[160:161], v[222:223], 0, s[12:13]
	s_mov_b32 m0, s66
	s_nop 0
	global_load_lds_dwordx4 v[160:161], off
	s_barrier
	s_waitcnt lgkmcnt(0)
	s_setprio 1
	s_waitcnt lgkmcnt(0)
	v_mfma_f32_16x16x32_bf16 v[60:63], v[128:131], v[168:171], v[60:63]
	v_mfma_f32_16x16x32_bf16 v[56:59], v[136:139], v[168:171], v[56:59]
	v_mfma_f32_16x16x32_bf16 v[44:47], v[128:131], v[176:179], v[44:47]
	v_mfma_f32_16x16x32_bf16 v[40:43], v[136:139], v[176:179], v[40:43]
	v_mfma_f32_16x16x32_bf16 v[28:31], v[128:131], v[186:189], v[28:31]
	v_mfma_f32_16x16x32_bf16 v[24:27], v[136:139], v[186:189], v[24:27]
	v_mfma_f32_16x16x32_bf16 v[12:15], v[128:131], v[194:197], v[12:15]
	v_mfma_f32_16x16x32_bf16 v[8:11], v[136:139], v[194:197], v[8:11]
	v_mfma_f32_16x16x32_bf16 v[60:63], v[132:135], v[172:175], v[60:63]
	v_mfma_f32_16x16x32_bf16 v[56:59], v[140:143], v[172:175], v[56:59]
	v_mfma_f32_16x16x32_bf16 v[44:47], v[132:135], v[182:185], v[44:47]
	v_mfma_f32_16x16x32_bf16 v[40:43], v[140:143], v[182:185], v[40:43]
	v_mfma_f32_16x16x32_bf16 v[28:31], v[132:135], v[190:193], v[28:31]
	v_mfma_f32_16x16x32_bf16 v[24:27], v[140:143], v[190:193], v[24:27]
	v_mfma_f32_16x16x32_bf16 v[12:15], v[132:135], v[198:201], v[12:15]
	v_mfma_f32_16x16x32_bf16 v[8:11], v[140:143], v[198:201], v[8:11]
	s_setprio 0
	s_barrier
	s_add_u32 s48, s48, 0x40080
	s_addc_u32 s49, s49, 0
	s_add_i32 s50, s50, s58
	v_lshl_add_u64 v[128:129], s[48:49], 0, v[146:147]
	s_mov_b32 m0, s50
	s_nop 0
	global_load_lds_dwordx4 v[128:129], off
	v_lshl_add_u64 v[128:129], s[48:49], 0, v[150:151]
	s_add_i32 m0, s50, 0x2000
	s_nop 0
	global_load_lds_dwordx4 v[128:129], off
	s_waitcnt vmcnt(6)
	s_barrier
	s_setprio 1
	v_mfma_f32_16x16x32_bf16 v[52:55], v[202:205], v[168:171], v[52:55]
	v_mfma_f32_16x16x32_bf16 v[48:51], v[210:213], v[168:171], v[48:51]
	v_mfma_f32_16x16x32_bf16 v[36:39], v[202:205], v[176:179], v[36:39]
	v_mfma_f32_16x16x32_bf16 v[32:35], v[210:213], v[176:179], v[32:35]
	v_mfma_f32_16x16x32_bf16 v[20:23], v[202:205], v[186:189], v[20:23]
	v_mfma_f32_16x16x32_bf16 v[16:19], v[210:213], v[186:189], v[16:19]
	v_mfma_f32_16x16x32_bf16 v[4:7], v[202:205], v[194:197], v[4:7]
	v_mfma_f32_16x16x32_bf16 v[0:3], v[210:213], v[194:197], v[0:3]
	v_mfma_f32_16x16x32_bf16 v[52:55], v[206:209], v[172:175], v[52:55]
	v_mfma_f32_16x16x32_bf16 v[48:51], v[214:217], v[172:175], v[48:51]
	v_mfma_f32_16x16x32_bf16 v[36:39], v[206:209], v[182:185], v[36:39]
	v_mfma_f32_16x16x32_bf16 v[32:35], v[214:217], v[182:185], v[32:35]
	v_mfma_f32_16x16x32_bf16 v[20:23], v[206:209], v[190:193], v[20:23]
	v_mfma_f32_16x16x32_bf16 v[16:19], v[214:217], v[190:193], v[16:19]
	v_mfma_f32_16x16x32_bf16 v[4:7], v[206:209], v[198:201], v[4:7]
	v_mfma_f32_16x16x32_bf16 v[0:3], v[214:217], v[198:201], v[0:3]
	s_setprio 0
	s_add_i32 s77, s77, 2
	s_add_u32 s46, s46, 0x100
	s_addc_u32 s47, s47, 0
	s_add_u32 s75, s75, 0x100
	s_addc_u32 s76, s76, 0
	s_cmp_gt_u32 s77, 13
	s_barrier
	s_cbranch_scc0 .LBB0_724
	v_lshl_add_u32 v171, s44, 8, v162
	v_lshl_or_b32 v172, s72, 8, v164
	s_ashr_i32 s25, s44, 4
	s_mul_hi_i32 s39, s25, 0x6000
	s_mulk_i32 s25, 0x6000
	s_add_u32 s46, s63, s25
	s_addc_u32 s47, s64, s39
	v_lshlrev_b32_e32 v168, 2, v172
	v_lshlrev_b32_e32 v160, 12, v171
	v_lshlrev_b32_e32 v161, 11, v171
	global_load_dwordx4 v[128:131], v168, s[46:47]
	global_load_dwordx4 v[132:135], v168, s[46:47] offset:16
	global_load_dwordx4 v[136:139], v168, s[46:47] offset:512
	global_load_dwordx4 v[140:143], v168, s[46:47] offset:528
	v_lshl_add_u32 v160, v172, 2, v160
	v_lshl_add_u32 v161, v172, 1, v161
	s_mov_b32 s72, s24
	s_mov_b32 s44, s38
	s_mov_b64 s[48:49], s[42:43]
	s_mov_b64 s[46:47], s[40:41]
	global_load_dwordx4 v[184:187], v160, s[36:37]
	global_load_dwordx4 v[188:191], v160, s[36:37] offset:16
	global_load_dwordx4 v[192:195], v160, s[36:37] offset:512
	global_load_dwordx4 v[196:199], v160, s[36:37] offset:528
	v_add_u32_e32 v169, 0x10000, v160
	global_load_dwordx4 v[200:203], v169, s[36:37]
	global_load_dwordx4 v[204:207], v169, s[36:37] offset:16
	v_add_u32_e32 v169, 0x10000, v160
	global_load_dwordx4 v[208:211], v169, s[36:37] offset:512
	global_load_dwordx4 v[212:215], v169, s[36:37] offset:528
	v_add_u32_e32 v169, 0x20000, v160
	global_load_dwordx4 v[216:219], v169, s[36:37]
	global_load_dwordx4 v[220:223], v169, s[36:37] offset:16
	v_add_u32_e32 v169, 0x20000, v160
	global_load_dwordx4 v[224:227], v169, s[36:37] offset:512
	global_load_dwordx4 v[228:231], v169, s[36:37] offset:528
	v_add_u32_e32 v169, 0x30000, v160
	global_load_dwordx4 v[232:235], v169, s[36:37]
	global_load_dwordx4 v[236:239], v169, s[36:37] offset:16
	v_add_u32_e32 v169, 0x30000, v160
	global_load_dwordx4 v[240:243], v169, s[36:37] offset:512
	global_load_dwordx4 v[244:247], v169, s[36:37] offset:528
	s_waitcnt vmcnt(14)
	v_pk_fma_f32 v[124:125], v[124:125], v[128:129], v[184:185]
	v_pk_fma_f32 v[126:127], v[126:127], v[130:131], v[186:187]
	v_pk_fma_f32 v[120:121], v[120:121], v[132:133], v[188:189]
	v_pk_fma_f32 v[122:123], v[122:123], v[134:135], v[190:191]
	v_add_u32_e32 v169, 0x80000, v160
	global_load_dwordx4 v[184:187], v169, s[36:37]
	global_load_dwordx4 v[188:191], v169, s[36:37] offset:16
	v_cvt_pk_bf16_f32 v124, v124, v125
	v_cvt_pk_bf16_f32 v125, v126, v127
	v_cvt_pk_bf16_f32 v126, v120, v121
	v_cvt_pk_bf16_f32 v127, v122, v123
	global_store_dwordx4 v161, v[124:127], s[8:9]
	s_waitcnt vmcnt(15)
; DI unsigned pk2(float a, float b) { f32x2 v = {a, b}; bf16x2_t r = __builtin_convertvector(v, bf16x2_t); return __builtin_bit_cast(unsigned, r); }
;     DI void operator()(const f32x4 (&acc)[2][2][4][2], const Unit& u, int wr, int wc, int fr, int fq) const {
;     ...
; #pragma unroll
;         for (int ai = 0; ai < 2; ++ai)
; #pragma unroll
;             for (int m = 0; m < 4; ++m) { const size_t ro = (size_t)(row0 + ai * HALF + m * 16) * DM + col0;
; #pragma unroll
;                 for (int bj = 0; bj < 2; ++bj) {
;                     const f32x4 x0 = *(const f32x4*)(base + ro + bj * HALF) + gv[bj][0] * acc[ai][bj][m][0], x1 = *(const f32x4*)(base + ro + bj * HALF + 4) + gv[bj][1] * acc[ai][bj][m][1];
;                     u32x4 w; w.x = pk2(x0.x, x0.y); w.y = pk2(x0.z, x0.w); w.z = pk2(x1.x, x1.y); w.w = pk2(x1.z, x1.w);
;                     *(u32x4*)(outb + ro + bj * HALF) = w; } }
	v_pk_fma_f32 v[116:117], v[116:117], v[136:137], v[192:193]
	v_pk_fma_f32 v[118:119], v[118:119], v[138:139], v[194:195]
	v_pk_fma_f32 v[112:113], v[112:113], v[140:141], v[196:197]
	v_pk_fma_f32 v[114:115], v[114:115], v[142:143], v[198:199]
	v_add_u32_e32 v169, 0x80000, v160
	global_load_dwordx4 v[192:195], v169, s[36:37] offset:512
	global_load_dwordx4 v[196:199], v169, s[36:37] offset:528
	v_cvt_pk_bf16_f32 v116, v116, v117
	v_cvt_pk_bf16_f32 v117, v118, v119
	v_cvt_pk_bf16_f32 v118, v112, v113
	v_cvt_pk_bf16_f32 v119, v114, v115
	global_store_dwordx4 v161, v[116:119], s[8:9] offset:256
	s_waitcnt vmcnt(16)
	v_pk_fma_f32 v[108:109], v[108:109], v[128:129], v[200:201]
	v_pk_fma_f32 v[110:111], v[110:111], v[130:131], v[202:203]
	v_pk_fma_f32 v[104:105], v[104:105], v[132:133], v[204:205]
	v_pk_fma_f32 v[106:107], v[106:107], v[134:135], v[206:207]
	v_add_u32_e32 v169, 0x90000, v160
	global_load_dwordx4 v[200:203], v169, s[36:37]
	global_load_dwordx4 v[204:207], v169, s[36:37] offset:16
	v_cvt_pk_bf16_f32 v108, v108, v109
	v_cvt_pk_bf16_f32 v109, v110, v111
	v_cvt_pk_bf16_f32 v110, v104, v105
	v_cvt_pk_bf16_f32 v111, v106, v107
	v_add_u32_e32 v170, 0x8000, v161
	global_store_dwordx4 v170, v[108:111], s[8:9]
	s_waitcnt vmcnt(17)
	v_pk_fma_f32 v[100:101], v[100:101], v[136:137], v[208:209]
	v_pk_fma_f32 v[102:103], v[102:103], v[138:139], v[210:211]
	v_pk_fma_f32 v[96:97], v[96:97], v[140:141], v[212:213]
	v_pk_fma_f32 v[98:99], v[98:99], v[142:143], v[214:215]
	v_add_u32_e32 v169, 0x90000, v160
	global_load_dwordx4 v[208:211], v169, s[36:37] offset:512
	global_load_dwordx4 v[212:215], v169, s[36:37] offset:528
	v_cvt_pk_bf16_f32 v100, v100, v101
	v_cvt_pk_bf16_f32 v101, v102, v103
	v_cvt_pk_bf16_f32 v102, v96, v97
	v_cvt_pk_bf16_f32 v103, v98, v99
	v_add_u32_e32 v170, 0x8000, v161
	global_store_dwordx4 v170, v[100:103], s[8:9] offset:256
	s_waitcnt vmcnt(18)
	v_pk_fma_f32 v[92:93], v[92:93], v[128:129], v[216:217]
	v_pk_fma_f32 v[94:95], v[94:95], v[130:131], v[218:219]
	v_pk_fma_f32 v[88:89], v[88:89], v[132:133], v[220:221]
	v_pk_fma_f32 v[90:91], v[90:91], v[134:135], v[222:223]
	v_add_u32_e32 v169, 0xa0000, v160
	global_load_dwordx4 v[216:219], v169, s[36:37]
	global_load_dwordx4 v[220:223], v169, s[36:37] offset:16
	v_cvt_pk_bf16_f32 v92, v92, v93
	v_cvt_pk_bf16_f32 v93, v94, v95
	v_cvt_pk_bf16_f32 v94, v88, v89
	v_cvt_pk_bf16_f32 v95, v90, v91
	v_add_u32_e32 v170, 0x10000, v161
	global_store_dwordx4 v170, v[92:95], s[8:9]
	s_waitcnt vmcnt(19)
	v_pk_fma_f32 v[84:85], v[84:85], v[136:137], v[224:225]
	v_pk_fma_f32 v[86:87], v[86:87], v[138:139], v[226:227]
	v_pk_fma_f32 v[80:81], v[80:81], v[140:141], v[228:229]
	v_pk_fma_f32 v[82:83], v[82:83], v[142:143], v[230:231]
	v_add_u32_e32 v169, 0xa0000, v160
	global_load_dwordx4 v[224:227], v169, s[36:37] offset:512
	global_load_dwordx4 v[228:231], v169, s[36:37] offset:528
	v_cvt_pk_bf16_f32 v84, v84, v85
	v_cvt_pk_bf16_f32 v85, v86, v87
	v_cvt_pk_bf16_f32 v86, v80, v81
	v_cvt_pk_bf16_f32 v87, v82, v83
	v_add_u32_e32 v170, 0x10000, v161
	global_store_dwordx4 v170, v[84:87], s[8:9] offset:256
	s_waitcnt vmcnt(20)
	v_pk_fma_f32 v[76:77], v[76:77], v[128:129], v[232:233]
	v_pk_fma_f32 v[78:79], v[78:79], v[130:131], v[234:235]
	v_pk_fma_f32 v[72:73], v[72:73], v[132:133], v[236:237]
	v_pk_fma_f32 v[74:75], v[74:75], v[134:135], v[238:239]
	v_add_u32_e32 v169, 0xb0000, v160
	global_load_dwordx4 v[232:235], v169, s[36:37]
	global_load_dwordx4 v[236:239], v169, s[36:37] offset:16
	v_cvt_pk_bf16_f32 v76, v76, v77
	v_cvt_pk_bf16_f32 v77, v78, v79
	v_cvt_pk_bf16_f32 v78, v72, v73
	v_cvt_pk_bf16_f32 v79, v74, v75
	v_add_u32_e32 v170, 0x18000, v161
	global_store_dwordx4 v170, v[76:79], s[8:9]
	s_waitcnt vmcnt(21)
	v_pk_fma_f32 v[68:69], v[68:69], v[136:137], v[240:241]
	v_pk_fma_f32 v[70:71], v[70:71], v[138:139], v[242:243]
	v_pk_fma_f32 v[64:65], v[64:65], v[140:141], v[244:245]
	v_pk_fma_f32 v[66:67], v[66:67], v[142:143], v[246:247]
	v_add_u32_e32 v169, 0xb0000, v160
	global_load_dwordx4 v[240:243], v169, s[36:37] offset:512
	global_load_dwordx4 v[244:247], v169, s[36:37] offset:528
	v_cvt_pk_bf16_f32 v68, v68, v69
	v_cvt_pk_bf16_f32 v69, v70, v71
	v_cvt_pk_bf16_f32 v70, v64, v65
	v_cvt_pk_bf16_f32 v71, v66, v67
	v_add_u32_e32 v170, 0x18000, v161
	global_store_dwordx4 v170, v[68:71], s[8:9] offset:256
	s_waitcnt vmcnt(22)
; DI unsigned pk2(float a, float b) { f32x2 v = {a, b}; bf16x2_t r = __builtin_convertvector(v, bf16x2_t); return __builtin_bit_cast(unsigned, r); }
;     DI void operator()(const f32x4 (&acc)[2][2][4][2], const Unit& u, int wr, int wc, int fr, int fq) const {
;     ...
; #pragma unroll
;         for (int ai = 0; ai < 2; ++ai)
; #pragma unroll
;             for (int m = 0; m < 4; ++m) { const size_t ro = (size_t)(row0 + ai * HALF + m * 16) * DM + col0;
; #pragma unroll
;                 for (int bj = 0; bj < 2; ++bj) {
;                     const f32x4 x0 = *(const f32x4*)(base + ro + bj * HALF) + gv[bj][0] * acc[ai][bj][m][0], x1 = *(const f32x4*)(base + ro + bj * HALF + 4) + gv[bj][1] * acc[ai][bj][m][1];
;                     u32x4 w; w.x = pk2(x0.x, x0.y); w.y = pk2(x0.z, x0.w); w.z = pk2(x1.x, x1.y); w.w = pk2(x1.z, x1.w);
;                     *(u32x4*)(outb + ro + bj * HALF) = w; } }
	v_pk_fma_f32 v[60:61], v[60:61], v[128:129], v[184:185]
	v_pk_fma_f32 v[62:63], v[62:63], v[130:131], v[186:187]
	v_pk_fma_f32 v[56:57], v[56:57], v[132:133], v[188:189]
	v_pk_fma_f32 v[58:59], v[58:59], v[134:135], v[190:191]
	v_cvt_pk_bf16_f32 v60, v60, v61
	v_cvt_pk_bf16_f32 v61, v62, v63
	v_cvt_pk_bf16_f32 v62, v56, v57
	v_cvt_pk_bf16_f32 v63, v58, v59
	v_add_u32_e32 v170, 0x40000, v161
	global_store_dwordx4 v170, v[60:63], s[8:9]
	s_waitcnt vmcnt(20)
	v_pk_fma_f32 v[52:53], v[52:53], v[136:137], v[192:193]
	v_pk_fma_f32 v[54:55], v[54:55], v[138:139], v[194:195]
	v_pk_fma_f32 v[48:49], v[48:49], v[140:141], v[196:197]
	v_pk_fma_f32 v[50:51], v[50:51], v[142:143], v[198:199]
	v_cvt_pk_bf16_f32 v52, v52, v53
	v_cvt_pk_bf16_f32 v53, v54, v55
	v_cvt_pk_bf16_f32 v54, v48, v49
	v_cvt_pk_bf16_f32 v55, v50, v51
	v_add_u32_e32 v170, 0x40000, v161
	global_store_dwordx4 v170, v[52:55], s[8:9] offset:256
	s_waitcnt vmcnt(18)
	v_pk_fma_f32 v[44:45], v[44:45], v[128:129], v[200:201]
	v_pk_fma_f32 v[46:47], v[46:47], v[130:131], v[202:203]
	v_pk_fma_f32 v[40:41], v[40:41], v[132:133], v[204:205]
	v_pk_fma_f32 v[42:43], v[42:43], v[134:135], v[206:207]
	v_cvt_pk_bf16_f32 v44, v44, v45
	v_cvt_pk_bf16_f32 v45, v46, v47
	v_cvt_pk_bf16_f32 v46, v40, v41
	v_cvt_pk_bf16_f32 v47, v42, v43
	v_add_u32_e32 v170, 0x48000, v161
	global_store_dwordx4 v170, v[44:47], s[8:9]
	s_waitcnt vmcnt(16)
	v_pk_fma_f32 v[36:37], v[36:37], v[136:137], v[208:209]
	v_pk_fma_f32 v[38:39], v[38:39], v[138:139], v[210:211]
	v_pk_fma_f32 v[32:33], v[32:33], v[140:141], v[212:213]
	v_pk_fma_f32 v[34:35], v[34:35], v[142:143], v[214:215]
	v_cvt_pk_bf16_f32 v36, v36, v37
	v_cvt_pk_bf16_f32 v37, v38, v39
	v_cvt_pk_bf16_f32 v38, v32, v33
	v_cvt_pk_bf16_f32 v39, v34, v35
	v_add_u32_e32 v170, 0x48000, v161
	global_store_dwordx4 v170, v[36:39], s[8:9] offset:256
	s_waitcnt vmcnt(14)
	v_pk_fma_f32 v[28:29], v[28:29], v[128:129], v[216:217]
	v_pk_fma_f32 v[30:31], v[30:31], v[130:131], v[218:219]
	v_pk_fma_f32 v[24:25], v[24:25], v[132:133], v[220:221]
	v_pk_fma_f32 v[26:27], v[26:27], v[134:135], v[222:223]
	v_cvt_pk_bf16_f32 v28, v28, v29
	v_cvt_pk_bf16_f32 v29, v30, v31
	v_cvt_pk_bf16_f32 v30, v24, v25
	v_cvt_pk_bf16_f32 v31, v26, v27
	v_add_u32_e32 v170, 0x50000, v161
	global_store_dwordx4 v170, v[28:31], s[8:9]
	s_waitcnt vmcnt(12)
	v_pk_fma_f32 v[20:21], v[20:21], v[136:137], v[224:225]
	v_pk_fma_f32 v[22:23], v[22:23], v[138:139], v[226:227]
	v_pk_fma_f32 v[16:17], v[16:17], v[140:141], v[228:229]
	v_pk_fma_f32 v[18:19], v[18:19], v[142:143], v[230:231]
	v_cvt_pk_bf16_f32 v20, v20, v21
	v_cvt_pk_bf16_f32 v21, v22, v23
	v_cvt_pk_bf16_f32 v22, v16, v17
	v_cvt_pk_bf16_f32 v23, v18, v19
	v_add_u32_e32 v170, 0x50000, v161
	global_store_dwordx4 v170, v[20:23], s[8:9] offset:256
	s_waitcnt vmcnt(10)
	v_pk_fma_f32 v[12:13], v[12:13], v[128:129], v[232:233]
	v_pk_fma_f32 v[14:15], v[14:15], v[130:131], v[234:235]
	v_pk_fma_f32 v[8:9], v[8:9], v[132:133], v[236:237]
	v_pk_fma_f32 v[10:11], v[10:11], v[134:135], v[238:239]
	v_cvt_pk_bf16_f32 v12, v12, v13
	v_cvt_pk_bf16_f32 v13, v14, v15
	v_cvt_pk_bf16_f32 v14, v8, v9
	v_cvt_pk_bf16_f32 v15, v10, v11
	v_add_u32_e32 v170, 0x58000, v161
	global_store_dwordx4 v170, v[12:15], s[8:9]
	s_waitcnt vmcnt(8)
	v_pk_fma_f32 v[4:5], v[4:5], v[136:137], v[240:241]
	v_pk_fma_f32 v[6:7], v[6:7], v[138:139], v[242:243]
	v_pk_fma_f32 v[0:1], v[0:1], v[140:141], v[244:245]
	v_pk_fma_f32 v[2:3], v[2:3], v[142:143], v[246:247]
	v_cvt_pk_bf16_f32 v4, v4, v5
	v_cvt_pk_bf16_f32 v5, v6, v7
	v_cvt_pk_bf16_f32 v6, v0, v1
	v_cvt_pk_bf16_f32 v7, v2, v3
	v_add_u32_e32 v170, 0x58000, v161
	global_store_dwordx4 v170, v[4:7], s[8:9] offset:256
	s_and_b64 vcc, exec, s[4:5]
	s_cbranch_vccz .LBB0_717
	s_waitcnt vmcnt(0)
	s_cmpk_gt_u32 s52, 0xff
	s_cbranch_scc1 .LBB0_728
	s_barrier

; #define PG8_STAGE(bufoff, gbase, voff) do { _Pragma("unroll") for (int _i = 0; _i < 2; ++_i) \
;         __builtin_amdgcn_global_load_lds((const unsigned*)((const char*)(gbase) + (voff)[_i]), (LAS unsigned*)(lds + (bufoff) + ldsw + _i * 8192), 16, 0, 0); } while (0)
; #define PG8_LDA(dst, b, h) do { _Pragma("unroll") for (int m = 0; m < 4; ++m) _Pragma("unroll") for (int k = 0; k < 2; ++k) dst[m][k] = *(const LAS bf16x8*)(lds + PG8_SA(b, h) + aoff + m * 2048 + k * 1024); } while (0)
; #define PG8_LDB(dst, b, h) do { _Pragma("unroll") for (int n = 0; n < 2; ++n) _Pragma("unroll") for (int k = 0; k < 2; ++k) dst[n][k] = *(const LAS bf16x8*)(lds + PG8_SB(b, h) + boff + n * 2048 + k * 1024); } while (0)
; #define PG8_MMA(ai, bj, At, Bt) do { __builtin_amdgcn_s_setprio(1); _Pragma("unroll") for (int m = 0; m < 4; ++m) _Pragma("unroll") for (int n = 0; n < 2; ++n) _Pragma("unroll") for (int k = 0; k < 2; ++k) \
;         acc[ai][bj][m][n] = __builtin_amdgcn_mfma_f32_16x16x32_bf16(Bt[n][k], At[m][k], acc[ai][bj][m][n], 0, 0, 0); __builtin_amdgcn_s_setprio(0); } while (0)
; #define PG8_WAIT_L(n) asm volatile("s_waitcnt lgkmcnt(" #n ")" ::: "memory")
; #define PG8_BAR __builtin_amdgcn_s_barrier()
; #define PG8_SCHED __builtin_amdgcn_sched_barrier(0)
; template <class Epi>
; DI void gemm_phase(LAS unsigned char* lds, const Gemm g, const StaticOrder& S, const Epi& E) {
;     ...
;             PG8_LDB(B0, 0, 0); PG8_SCHED; PG8_LDA(At, 0, 0); PG8_STAGE(PG8_SA(1, 1), a1 + hstep, voffA);
;             PG8_WAIT_L(8); PG8_BAR; PG8_WAIT_L(0); PG8_MMA(0, 0, At, B0); PG8_BAR; PG8_SCHED;
;             PG8_LDB(B1, 0, 1); PG8_STAGE(PG8_SB(0, 0), b2, voffB);
;             PG8_BAR; PG8_WAIT_L(0); PG8_MMA(0, 1, At, B1); PG8_BAR;
;             PG8_LDA(At, 0, 1); PG8_STAGE(PG8_SA(0, 0), a2, voffA);
;             PG8_BAR; PG8_WAIT_L(0); PG8_MMA(1, 0, At, B0); PG8_BAR; PG8_SCHED;
.LBB0_928:
	ds_read_b128 v[128:131], v173
	ds_read_b128 v[132:135], v173 offset:1024
	ds_read_b128 v[136:139], v173 offset:2048
	ds_read_b128 v[140:143], v173 offset:3072
	s_add_u32 s38, s36, 0xfff50080
	s_addc_u32 s39, s37, -1
	s_cmp_eq_u32 s73, 40
	s_cselect_b32 s41, s7, s39
	s_cselect_b32 s40, s6, s38
	s_cselect_b32 s39, s9, s72
	s_cselect_b32 s38, s8, s71
	v_lshl_add_u64 v[168:169], s[36:37], 0, v[156:157]
	s_add_i32 m0, s49, 0xc000
	ds_read_b128 v[144:147], v174
	ds_read_b128 v[164:167], v174 offset:1024
	ds_read_b128 v[176:179], v174 offset:2048
	ds_read_b128 v[182:185], v174 offset:3072
	ds_read_b128 v[186:189], v174 offset:4096
	ds_read_b128 v[190:193], v174 offset:5120
	ds_read_b128 v[194:197], v174 offset:6144
	ds_read_b128 v[198:201], v174 offset:7168
	global_load_lds_dwordx4 v[168:169], off
	v_lshl_add_u64 v[168:169], s[36:37], 0, v[158:159]
	s_add_i32 m0, s49, 0xe000
	s_nop 0
	global_load_lds_dwordx4 v[168:169], off
	s_waitcnt lgkmcnt(8)
	s_barrier
	s_waitcnt lgkmcnt(0)
	s_setprio 1
	s_waitcnt lgkmcnt(0)
	v_mfma_f32_16x16x32_bf16 v[124:127], v[128:131], v[144:147], v[124:127]
	v_mfma_f32_16x16x32_bf16 v[120:123], v[136:139], v[144:147], v[120:123]
	v_mfma_f32_16x16x32_bf16 v[116:119], v[128:131], v[176:179], v[116:119]
	v_mfma_f32_16x16x32_bf16 v[108:111], v[136:139], v[176:179], v[108:111]
	v_mfma_f32_16x16x32_bf16 v[92:95], v[128:131], v[186:189], v[92:95]
	v_mfma_f32_16x16x32_bf16 v[88:91], v[136:139], v[186:189], v[88:91]
	v_mfma_f32_16x16x32_bf16 v[76:79], v[128:131], v[194:197], v[76:79]
	v_mfma_f32_16x16x32_bf16 v[72:75], v[136:139], v[194:197], v[72:75]
	v_mfma_f32_16x16x32_bf16 v[124:127], v[132:135], v[164:167], v[124:127]
	v_mfma_f32_16x16x32_bf16 v[120:123], v[140:143], v[164:167], v[120:123]
	v_mfma_f32_16x16x32_bf16 v[116:119], v[132:135], v[182:185], v[116:119]
	v_mfma_f32_16x16x32_bf16 v[108:111], v[140:143], v[182:185], v[108:111]
	v_mfma_f32_16x16x32_bf16 v[92:95], v[132:135], v[190:193], v[92:95]
	v_mfma_f32_16x16x32_bf16 v[88:91], v[140:143], v[190:193], v[88:91]
	v_mfma_f32_16x16x32_bf16 v[76:79], v[132:135], v[198:201], v[76:79]
	v_mfma_f32_16x16x32_bf16 v[72:75], v[140:143], v[198:201], v[72:75]
	s_setprio 0
	s_barrier
	s_add_i32 s74, s59, s48
	v_lshl_add_u64 v[168:169], s[38:39], 0, v[150:151]
	s_mov_b32 m0, s74
	ds_read_b128 v[202:205], v175
	ds_read_b128 v[206:209], v175 offset:1024
	ds_read_b128 v[210:213], v175 offset:2048
	ds_read_b128 v[214:217], v175 offset:3072
	global_load_lds_dwordx4 v[168:169], off
	v_lshl_add_u64 v[218:219], s[38:39], 0, v[154:155]
	s_add_i32 m0, s74, 0x2000
	s_nop 0
	global_load_lds_dwordx4 v[218:219], off
	s_barrier
	s_waitcnt lgkmcnt(0)
	s_setprio 1
	s_waitcnt lgkmcnt(0)
	v_mfma_f32_16x16x32_bf16 v[112:115], v[202:205], v[144:147], v[112:115]
	v_mfma_f32_16x16x32_bf16 v[104:107], v[210:213], v[144:147], v[104:107]
	v_mfma_f32_16x16x32_bf16 v[100:103], v[202:205], v[176:179], v[100:103]
	v_mfma_f32_16x16x32_bf16 v[96:99], v[210:213], v[176:179], v[96:99]
	v_mfma_f32_16x16x32_bf16 v[84:87], v[202:205], v[186:189], v[84:87]
	v_mfma_f32_16x16x32_bf16 v[80:83], v[210:213], v[186:189], v[80:83]
	v_mfma_f32_16x16x32_bf16 v[68:71], v[202:205], v[194:197], v[68:71]
	v_mfma_f32_16x16x32_bf16 v[64:67], v[210:213], v[194:197], v[64:67]
	v_mfma_f32_16x16x32_bf16 v[112:115], v[206:209], v[164:167], v[112:115]
	v_mfma_f32_16x16x32_bf16 v[104:107], v[214:217], v[164:167], v[104:107]
	v_mfma_f32_16x16x32_bf16 v[100:103], v[206:209], v[182:185], v[100:103]
	v_mfma_f32_16x16x32_bf16 v[96:99], v[214:217], v[182:185], v[96:99]
	v_mfma_f32_16x16x32_bf16 v[84:87], v[206:209], v[190:193], v[84:87]
	v_mfma_f32_16x16x32_bf16 v[80:83], v[214:217], v[190:193], v[80:83]
	v_mfma_f32_16x16x32_bf16 v[68:71], v[206:209], v[198:201], v[68:71]
	v_mfma_f32_16x16x32_bf16 v[64:67], v[214:217], v[198:201], v[64:67]
	s_setprio 0
	s_mov_b32 m0, s49
	v_lshl_add_u64 v[220:221], s[40:41], 0, v[148:149]
	s_barrier
	ds_read_b128 v[144:147], v174 offset:16384
	ds_read_b128 v[164:167], v174 offset:17408
	ds_read_b128 v[176:179], v174 offset:18432
	ds_read_b128 v[182:185], v174 offset:19456
	ds_read_b128 v[186:189], v174 offset:20480
	ds_read_b128 v[190:193], v174 offset:21504
	ds_read_b128 v[194:197], v174 offset:22528
	ds_read_b128 v[198:201], v174 offset:23552
	global_load_lds_dwordx4 v[220:221], off
	v_lshl_add_u64 v[222:223], s[40:41], 0, v[152:153]
	s_mov_b32 m0, s50
	s_nop 0
	global_load_lds_dwordx4 v[222:223], off
	s_barrier
	s_waitcnt lgkmcnt(0)
	s_setprio 1
	s_waitcnt lgkmcnt(0)
	v_mfma_f32_16x16x32_bf16 v[60:63], v[128:131], v[144:147], v[60:63]
	v_mfma_f32_16x16x32_bf16 v[56:59], v[136:139], v[144:147], v[56:59]
	v_mfma_f32_16x16x32_bf16 v[44:47], v[128:131], v[176:179], v[44:47]
	v_mfma_f32_16x16x32_bf16 v[40:43], v[136:139], v[176:179], v[40:43]
	v_mfma_f32_16x16x32_bf16 v[36:39], v[128:131], v[186:189], v[36:39]
	v_mfma_f32_16x16x32_bf16 v[32:35], v[136:139], v[186:189], v[32:35]
	v_mfma_f32_16x16x32_bf16 v[20:23], v[128:131], v[194:197], v[20:23]
	v_mfma_f32_16x16x32_bf16 v[16:19], v[136:139], v[194:197], v[16:19]
	v_mfma_f32_16x16x32_bf16 v[60:63], v[132:135], v[164:167], v[60:63]
	v_mfma_f32_16x16x32_bf16 v[56:59], v[140:143], v[164:167], v[56:59]
	v_mfma_f32_16x16x32_bf16 v[44:47], v[132:135], v[182:185], v[44:47]
	v_mfma_f32_16x16x32_bf16 v[40:43], v[140:143], v[182:185], v[40:43]
	v_mfma_f32_16x16x32_bf16 v[36:39], v[132:135], v[190:193], v[36:39]
	v_mfma_f32_16x16x32_bf16 v[32:35], v[140:143], v[190:193], v[32:35]
	v_mfma_f32_16x16x32_bf16 v[20:23], v[132:135], v[198:201], v[20:23]
	v_mfma_f32_16x16x32_bf16 v[16:19], v[140:143], v[198:201], v[16:19]
	s_setprio 0
	s_barrier
; #define PG8_STAGE(bufoff, gbase, voff) do { _Pragma("unroll") for (int _i = 0; _i < 2; ++_i) \
;         __builtin_amdgcn_global_load_lds((const unsigned*)((const char*)(gbase) + (voff)[_i]), (LAS unsigned*)(lds + (bufoff) + ldsw + _i * 8192), 16, 0, 0); } while (0)
; #define PG8_LDA(dst, b, h) do { _Pragma("unroll") for (int m = 0; m < 4; ++m) _Pragma("unroll") for (int k = 0; k < 2; ++k) dst[m][k] = *(const LAS bf16x8*)(lds + PG8_SA(b, h) + aoff + m * 2048 + k * 1024); } while (0)
; #define PG8_LDB(dst, b, h) do { _Pragma("unroll") for (int n = 0; n < 2; ++n) _Pragma("unroll") for (int k = 0; k < 2; ++k) dst[n][k] = *(const LAS bf16x8*)(lds + PG8_SB(b, h) + boff + n * 2048 + k * 1024); } while (0)
; #define PG8_MMA(ai, bj, At, Bt) do { __builtin_amdgcn_s_setprio(1); _Pragma("unroll") for (int m = 0; m < 4; ++m) _Pragma("unroll") for (int n = 0; n < 2; ++n) _Pragma("unroll") for (int k = 0; k < 2; ++k) \
;         acc[ai][bj][m][n] = __builtin_amdgcn_mfma_f32_16x16x32_bf16(Bt[n][k], At[m][k], acc[ai][bj][m][n], 0, 0, 0); __builtin_amdgcn_s_setprio(0); } while (0)
; #define PG8_WAIT_V(n) asm volatile("s_waitcnt vmcnt(" #n ")" ::: "memory")
; #define PG8_WAIT_L(n) asm volatile("s_waitcnt lgkmcnt(" #n ")" ::: "memory")
; #define PG8_BAR __builtin_amdgcn_s_barrier()
; #define PG8_SCHED __builtin_amdgcn_sched_barrier(0)
; template <class Epi>
; DI void gemm_phase(LAS unsigned char* lds, const Gemm g, const StaticOrder& S, const Epi& E) {
;     ...
;             PG8_STAGE(PG8_SB(0, 1), b2 + hstep, voffB);
;             PG8_WAIT_V(6); PG8_BAR; PG8_MMA(1, 1, At, B1); PG8_BAR;
;             PG8_LDB(B0, 1, 0); PG8_SCHED; PG8_LDA(At, 1, 0); PG8_STAGE(PG8_SA(0, 1), a2 + hstep, voffA);
;             PG8_WAIT_L(8); PG8_BAR; PG8_WAIT_L(0); PG8_MMA(0, 0, At, B0); PG8_BAR; PG8_SCHED;
;             PG8_LDB(B1, 1, 1); PG8_STAGE(PG8_SB(1, 0), b3, voffB);
;             PG8_BAR; PG8_WAIT_L(0); PG8_MMA(0, 1, At, B1); PG8_BAR;
;             PG8_LDA(At, 1, 1); PG8_STAGE(PG8_SA(1, 0), a3, voffA);
;             PG8_BAR; PG8_WAIT_L(0); PG8_MMA(1, 0, At, B0); PG8_BAR; PG8_SCHED;
	s_add_u32 s74, s38, 0xb0000
	s_addc_u32 s75, s39, 0
	s_add_i32 s76, s60, s48
	v_lshl_add_u64 v[128:129], s[74:75], 0, v[150:151]
	s_mov_b32 m0, s76
	s_nop 0
	global_load_lds_dwordx4 v[128:129], off
	v_lshl_add_u64 v[128:129], s[74:75], 0, v[154:155]
	s_add_i32 m0, s76, 0x2000
	s_nop 0
	global_load_lds_dwordx4 v[128:129], off
	s_waitcnt vmcnt(6)
	s_barrier
	s_setprio 1
	v_mfma_f32_16x16x32_bf16 v[52:55], v[202:205], v[144:147], v[52:55]
	v_mfma_f32_16x16x32_bf16 v[48:51], v[210:213], v[144:147], v[48:51]
	v_mfma_f32_16x16x32_bf16 v[28:31], v[202:205], v[176:179], v[28:31]
	v_mfma_f32_16x16x32_bf16 v[24:27], v[210:213], v[176:179], v[24:27]
	v_mfma_f32_16x16x32_bf16 v[12:15], v[202:205], v[186:189], v[12:15]
	v_mfma_f32_16x16x32_bf16 v[8:11], v[210:213], v[186:189], v[8:11]
	v_mfma_f32_16x16x32_bf16 v[4:7], v[202:205], v[194:197], v[4:7]
	v_mfma_f32_16x16x32_bf16 v[0:3], v[210:213], v[194:197], v[0:3]
	v_mfma_f32_16x16x32_bf16 v[52:55], v[206:209], v[164:167], v[52:55]
	v_mfma_f32_16x16x32_bf16 v[48:51], v[214:217], v[164:167], v[48:51]
	v_mfma_f32_16x16x32_bf16 v[28:31], v[206:209], v[182:185], v[28:31]
	v_mfma_f32_16x16x32_bf16 v[24:27], v[214:217], v[182:185], v[24:27]
	v_mfma_f32_16x16x32_bf16 v[12:15], v[206:209], v[190:193], v[12:15]
	v_mfma_f32_16x16x32_bf16 v[8:11], v[214:217], v[190:193], v[8:11]
	v_mfma_f32_16x16x32_bf16 v[4:7], v[206:209], v[198:201], v[4:7]
	v_mfma_f32_16x16x32_bf16 v[0:3], v[214:217], v[198:201], v[0:3]
	s_setprio 0
	s_add_i32 s74, 0, 0x18000
	v_add_u32_e32 v140, s74, v171
	s_barrier
	ds_read_b128 v[128:131], v140
	ds_read_b128 v[132:135], v140 offset:1024
	ds_read_b128 v[136:139], v140 offset:2048
	ds_read_b128 v[140:143], v140 offset:3072
	s_add_u32 s40, s40, 0xb0000
	s_addc_u32 s41, s41, 0
	s_mov_b32 m0, s51
	v_lshl_add_u64 v[202:203], s[40:41], 0, v[148:149]
	ds_read_b128 v[144:147], v174 offset:32768
	ds_read_b128 v[164:167], v174 offset:33792
	ds_read_b128 v[176:179], v174 offset:34816
	ds_read_b128 v[182:185], v174 offset:35840
	ds_read_b128 v[186:189], v174 offset:36864
	ds_read_b128 v[190:193], v174 offset:37888
	ds_read_b128 v[194:197], v174 offset:38912
	ds_read_b128 v[198:201], v174 offset:39936
	global_load_lds_dwordx4 v[202:203], off
	v_lshl_add_u64 v[202:203], s[40:41], 0, v[152:153]
	s_mov_b32 m0, s52
	s_nop 0
	global_load_lds_dwordx4 v[202:203], off
	s_waitcnt lgkmcnt(8)
	s_barrier
	s_waitcnt lgkmcnt(0)
	s_setprio 1
	s_waitcnt lgkmcnt(0)
	v_mfma_f32_16x16x32_bf16 v[124:127], v[128:131], v[144:147], v[124:127]
	v_mfma_f32_16x16x32_bf16 v[120:123], v[136:139], v[144:147], v[120:123]
	v_mfma_f32_16x16x32_bf16 v[116:119], v[128:131], v[176:179], v[116:119]
	v_mfma_f32_16x16x32_bf16 v[108:111], v[136:139], v[176:179], v[108:111]
	v_mfma_f32_16x16x32_bf16 v[92:95], v[128:131], v[186:189], v[92:95]
	v_mfma_f32_16x16x32_bf16 v[88:91], v[136:139], v[186:189], v[88:91]
	v_mfma_f32_16x16x32_bf16 v[76:79], v[128:131], v[194:197], v[76:79]
	v_mfma_f32_16x16x32_bf16 v[72:75], v[136:139], v[194:197], v[72:75]
	v_mfma_f32_16x16x32_bf16 v[124:127], v[132:135], v[164:167], v[124:127]
	v_mfma_f32_16x16x32_bf16 v[120:123], v[140:143], v[164:167], v[120:123]
	v_mfma_f32_16x16x32_bf16 v[116:119], v[132:135], v[182:185], v[116:119]
	v_mfma_f32_16x16x32_bf16 v[108:111], v[140:143], v[182:185], v[108:111]
	v_mfma_f32_16x16x32_bf16 v[92:95], v[132:135], v[190:193], v[92:95]
	v_mfma_f32_16x16x32_bf16 v[88:91], v[140:143], v[190:193], v[88:91]
	v_mfma_f32_16x16x32_bf16 v[76:79], v[132:135], v[198:201], v[76:79]
	v_mfma_f32_16x16x32_bf16 v[72:75], v[140:143], v[198:201], v[72:75]
	s_setprio 0
	s_barrier
	s_add_i32 s40, 0, 0x1c000
	s_add_i32 s41, s74, s48
	v_add_u32_e32 v214, s40, v171
	v_lshl_add_u64 v[168:169], v[168:169], 0, s[16:17]
	s_mov_b32 m0, s41
	ds_read_b128 v[202:205], v214
	ds_read_b128 v[206:209], v214 offset:1024
	ds_read_b128 v[210:213], v214 offset:2048
	ds_read_b128 v[214:217], v214 offset:3072
	global_load_lds_dwordx4 v[168:169], off
	v_lshl_add_u64 v[168:169], v[218:219], 0, s[16:17]
	s_add_i32 m0, s41, 0x2000
	s_nop 0
	global_load_lds_dwordx4 v[168:169], off
	s_barrier
	s_waitcnt lgkmcnt(0)
	s_setprio 1
	s_waitcnt lgkmcnt(0)
	v_mfma_f32_16x16x32_bf16 v[112:115], v[202:205], v[144:147], v[112:115]
	v_mfma_f32_16x16x32_bf16 v[104:107], v[210:213], v[144:147], v[104:107]
	v_mfma_f32_16x16x32_bf16 v[100:103], v[202:205], v[176:179], v[100:103]
	v_mfma_f32_16x16x32_bf16 v[96:99], v[210:213], v[176:179], v[96:99]
	v_mfma_f32_16x16x32_bf16 v[84:87], v[202:205], v[186:189], v[84:87]
	v_mfma_f32_16x16x32_bf16 v[80:83], v[210:213], v[186:189], v[80:83]
	v_mfma_f32_16x16x32_bf16 v[68:71], v[202:205], v[194:197], v[68:71]
	v_mfma_f32_16x16x32_bf16 v[64:67], v[210:213], v[194:197], v[64:67]
	v_mfma_f32_16x16x32_bf16 v[112:115], v[206:209], v[164:167], v[112:115]
	v_mfma_f32_16x16x32_bf16 v[104:107], v[214:217], v[164:167], v[104:107]
	v_mfma_f32_16x16x32_bf16 v[100:103], v[206:209], v[182:185], v[100:103]
	v_mfma_f32_16x16x32_bf16 v[96:99], v[214:217], v[182:185], v[96:99]
	v_mfma_f32_16x16x32_bf16 v[84:87], v[206:209], v[190:193], v[84:87]
	v_mfma_f32_16x16x32_bf16 v[80:83], v[214:217], v[190:193], v[80:83]
	v_mfma_f32_16x16x32_bf16 v[68:71], v[206:209], v[198:201], v[68:71]
	v_mfma_f32_16x16x32_bf16 v[64:67], v[214:217], v[198:201], v[64:67]
	s_setprio 0
	s_mov_b32 m0, s56
	v_lshl_add_u64 v[168:169], v[220:221], 0, s[16:17]
	s_barrier
	ds_read_b128 v[144:147], v174 offset:49152
	ds_read_b128 v[164:167], v174 offset:50176
	ds_read_b128 v[176:179], v174 offset:51200
	ds_read_b128 v[182:185], v174 offset:52224
	ds_read_b128 v[186:189], v174 offset:53248
	ds_read_b128 v[190:193], v174 offset:54272
	ds_read_b128 v[194:197], v174 offset:55296
	ds_read_b128 v[198:201], v174 offset:56320
	global_load_lds_dwordx4 v[168:169], off
	v_lshl_add_u64 v[168:169], v[222:223], 0, s[16:17]
	s_mov_b32 m0, s57
	s_nop 0
	global_load_lds_dwordx4 v[168:169], off
	s_barrier
; DI unsigned pk2(float a, float b) { f32x2 v = {a, b}; bf16x2_t r = __builtin_convertvector(v, bf16x2_t); return __builtin_bit_cast(unsigned, r); }
; DI float bflo(unsigned u) { return __uint_as_float(u << 16); }
; DI float bfhi(unsigned u) { return __uint_as_float(u & 0xffff0000u); }
; #define PG8_STAGE(bufoff, gbase, voff) do { _Pragma("unroll") for (int _i = 0; _i < 2; ++_i) \
;         __builtin_amdgcn_global_load_lds((const unsigned*)((const char*)(gbase) + (voff)[_i]), (LAS unsigned*)(lds + (bufoff) + ldsw + _i * 8192), 16, 0, 0); } while (0)
; #define PG8_WAIT_V(n) asm volatile("s_waitcnt vmcnt(" #n ")" ::: "memory")
; #define PG8_WAIT_L(n) asm volatile("s_waitcnt lgkmcnt(" #n ")" ::: "memory")
; template <class Epi>
; DI void gemm_phase(LAS unsigned char* lds, const Gemm g, const StaticOrder& S, const Epi& E) {
;     ...
;             PG8_LDA(At, 1, 1); PG8_STAGE(PG8_SA(1, 0), a3, voffA);
;             PG8_BAR; PG8_WAIT_L(0); PG8_MMA(1, 0, At, B0); PG8_BAR; PG8_SCHED;
;             PG8_STAGE(PG8_SB(1, 1), b3 + hstep, voffB);
;             PG8_WAIT_V(6); PG8_BAR; PG8_MMA(1, 1, At, B1); PG8_BAR;
;     DI void operator()(const f32x4 (&acc)[2][2][4][2], const Unit& u, int wr, int wc, int fr, int fq) const {
;         const int row0 = u.pm * BM + wr * 64 + fr, col0 = u.pn * BM + wc * 32 + 8 * fq;
;         const float* gp = gate + (size_t)((u.pm * BM) >> 12) * NMODC + col0;
;         f32x4 gv[2][2];
; #pragma unroll
;         for (int bj = 0; bj < 2; ++bj)
; #pragma unroll
;             for (int n = 0; n < 2; ++n) gv[bj][n] = *(const f32x4*)(gp + bj * HALF + n * 4);
; #pragma unroll
;         for (int ai = 0; ai < 2; ++ai)
; #pragma unroll
;             for (int m = 0; m < 4; ++m) { const size_t ro = (size_t)(row0 + ai * HALF + m * 16) * DM + col0;
; #pragma unroll
;                 for (int bj = 0; bj < 2; ++bj) {
;                     const u32x4 q = *(const u32x4*)(xb + ro + bj * HALF);
;                     const f32x4 b0 = {bflo(q.x), bfhi(q.x), bflo(q.y), bfhi(q.y)}, b1 = {bflo(q.z), bfhi(q.z), bflo(q.w), bfhi(q.w)};
;                     const f32x4 x0 = b0 + gv[bj][0] * acc[ai][bj][m][0], x1 = b1 + gv[bj][1] * acc[ai][bj][m][1];
;                     u32x4 w; w.x = pk2(x0.x, x0.y); w.y = pk2(x0.z, x0.w); w.z = pk2(x1.x, x1.y); w.w = pk2(x1.z, x1.w);
;                     *(u32x4*)(xb + ro + bj * HALF) = w; } }
	s_waitcnt lgkmcnt(0)
	s_setprio 1
	s_waitcnt lgkmcnt(0)
	v_mfma_f32_16x16x32_bf16 v[60:63], v[128:131], v[144:147], v[60:63]
	v_mfma_f32_16x16x32_bf16 v[56:59], v[136:139], v[144:147], v[56:59]
	v_mfma_f32_16x16x32_bf16 v[44:47], v[128:131], v[176:179], v[44:47]
	v_mfma_f32_16x16x32_bf16 v[40:43], v[136:139], v[176:179], v[40:43]
	v_mfma_f32_16x16x32_bf16 v[36:39], v[128:131], v[186:189], v[36:39]
	v_mfma_f32_16x16x32_bf16 v[32:35], v[136:139], v[186:189], v[32:35]
	v_mfma_f32_16x16x32_bf16 v[20:23], v[128:131], v[194:197], v[20:23]
	v_mfma_f32_16x16x32_bf16 v[16:19], v[136:139], v[194:197], v[16:19]
	v_mfma_f32_16x16x32_bf16 v[60:63], v[132:135], v[164:167], v[60:63]
	v_mfma_f32_16x16x32_bf16 v[56:59], v[140:143], v[164:167], v[56:59]
	v_mfma_f32_16x16x32_bf16 v[44:47], v[132:135], v[182:185], v[44:47]
	v_mfma_f32_16x16x32_bf16 v[40:43], v[140:143], v[182:185], v[40:43]
	v_mfma_f32_16x16x32_bf16 v[36:39], v[132:135], v[190:193], v[36:39]
	v_mfma_f32_16x16x32_bf16 v[32:35], v[140:143], v[190:193], v[32:35]
	v_mfma_f32_16x16x32_bf16 v[20:23], v[132:135], v[198:201], v[20:23]
	v_mfma_f32_16x16x32_bf16 v[16:19], v[140:143], v[198:201], v[16:19]
	s_setprio 0
	s_barrier
	s_add_u32 s38, s38, 0xb0080
	s_addc_u32 s39, s39, 0
	s_add_i32 s40, s40, s48
	v_lshl_add_u64 v[128:129], s[38:39], 0, v[150:151]
	s_mov_b32 m0, s40
	s_nop 0
	global_load_lds_dwordx4 v[128:129], off
	v_lshl_add_u64 v[128:129], s[38:39], 0, v[154:155]
	s_add_i32 m0, s40, 0x2000
	s_nop 0
	global_load_lds_dwordx4 v[128:129], off
	s_waitcnt vmcnt(6)
	s_barrier
	s_setprio 1
	v_mfma_f32_16x16x32_bf16 v[52:55], v[202:205], v[144:147], v[52:55]
	v_mfma_f32_16x16x32_bf16 v[48:51], v[210:213], v[144:147], v[48:51]
	v_mfma_f32_16x16x32_bf16 v[28:31], v[202:205], v[176:179], v[28:31]
	v_mfma_f32_16x16x32_bf16 v[24:27], v[210:213], v[176:179], v[24:27]
	v_mfma_f32_16x16x32_bf16 v[12:15], v[202:205], v[186:189], v[12:15]
	v_mfma_f32_16x16x32_bf16 v[8:11], v[210:213], v[186:189], v[8:11]
	v_mfma_f32_16x16x32_bf16 v[4:7], v[202:205], v[194:197], v[4:7]
	v_mfma_f32_16x16x32_bf16 v[0:3], v[210:213], v[194:197], v[0:3]
	v_mfma_f32_16x16x32_bf16 v[52:55], v[206:209], v[164:167], v[52:55]
	v_mfma_f32_16x16x32_bf16 v[48:51], v[214:217], v[164:167], v[48:51]
	v_mfma_f32_16x16x32_bf16 v[28:31], v[206:209], v[182:185], v[28:31]
	v_mfma_f32_16x16x32_bf16 v[24:27], v[214:217], v[182:185], v[24:27]
	v_mfma_f32_16x16x32_bf16 v[12:15], v[206:209], v[190:193], v[12:15]
	v_mfma_f32_16x16x32_bf16 v[8:11], v[214:217], v[190:193], v[8:11]
	v_mfma_f32_16x16x32_bf16 v[4:7], v[206:209], v[198:201], v[4:7]
	v_mfma_f32_16x16x32_bf16 v[0:3], v[214:217], v[198:201], v[0:3]
	s_setprio 0
	s_add_i32 s73, s73, 2
	s_add_u32 s36, s36, 0x100
	s_addc_u32 s37, s37, 0
	s_add_u32 s71, s71, 0x100
	s_addc_u32 s72, s72, 0
	s_cmp_gt_u32 s73, 41
	s_barrier
	s_cbranch_scc0 .LBB0_928
	v_lshl_add_u32 v147, s67, 8, v170
	v_lshl_or_b32 v164, s70, 8, v172
	s_ashr_i32 s36, s67, 4
	s_mul_hi_i32 s37, s36, 0x6000
	s_mulk_i32 s36, 0x6000
	s_add_u32 s36, s54, s36
	s_addc_u32 s37, s55, s37
	v_lshlrev_b32_e32 v145, 2, v164
	v_lshlrev_b32_e32 v144, 11, v147
	global_load_dwordx4 v[128:131], v145, s[36:37]
	global_load_dwordx4 v[132:135], v145, s[36:37] offset:16
	global_load_dwordx4 v[136:139], v145, s[36:37] offset:512
	global_load_dwordx4 v[140:143], v145, s[36:37] offset:528
	v_lshl_add_u32 v144, v164, 1, v144
	s_mov_b32 s70, s65
	s_mov_b32 s67, s66
	s_mov_b64 s[38:39], s[8:9]
	s_mov_b64 s[36:37], s[6:7]
	global_load_dwordx4 v[184:187], v144, s[14:15]
	global_load_dwordx4 v[188:191], v144, s[14:15] offset:256
	v_add_u32_e32 v146, 0x8000, v144
	global_load_dwordx4 v[192:195], v146, s[14:15]
	global_load_dwordx4 v[196:199], v146, s[14:15] offset:256
	v_add_u32_e32 v146, 0x10000, v144
	global_load_dwordx4 v[200:203], v146, s[14:15]
	global_load_dwordx4 v[204:207], v146, s[14:15] offset:256
	v_add_u32_e32 v146, 0x18000, v144
	global_load_dwordx4 v[208:211], v146, s[14:15]
	global_load_dwordx4 v[212:215], v146, s[14:15] offset:256
	v_add_u32_e32 v146, 0x40000, v144
	global_load_dwordx4 v[216:219], v146, s[14:15]
	global_load_dwordx4 v[220:223], v146, s[14:15] offset:256
	v_add_u32_e32 v146, 0x48000, v144
	global_load_dwordx4 v[224:227], v146, s[14:15]
	global_load_dwordx4 v[228:231], v146, s[14:15] offset:256
	v_add_u32_e32 v146, 0x50000, v144
	global_load_dwordx4 v[232:235], v146, s[14:15]
	global_load_dwordx4 v[236:239], v146, s[14:15] offset:256
	v_add_u32_e32 v146, 0x58000, v144
	global_load_dwordx4 v[240:243], v146, s[14:15]
	global_load_dwordx4 v[244:247], v146, s[14:15] offset:256
	s_waitcnt vmcnt(15)
	v_lshlrev_b32_e32 v248, 16, v184
	v_and_b32_e32 v249, 0xffff0000, v184
	v_lshlrev_b32_e32 v250, 16, v185
	v_and_b32_e32 v251, 0xffff0000, v185
	v_lshlrev_b32_e32 v252, 16, v186
	v_and_b32_e32 v253, 0xffff0000, v186
	v_lshlrev_b32_e32 v254, 16, v187
	v_and_b32_e32 v255, 0xffff0000, v187
	v_pk_fma_f32 v[124:125], v[124:125], v[128:129], v[248:249]
	v_pk_fma_f32 v[126:127], v[126:127], v[130:131], v[250:251]
	v_pk_fma_f32 v[120:121], v[120:121], v[132:133], v[252:253]
	v_pk_fma_f32 v[122:123], v[122:123], v[134:135], v[254:255]
	v_cvt_pk_bf16_f32 v124, v124, v125
	v_cvt_pk_bf16_f32 v125, v126, v127
	v_cvt_pk_bf16_f32 v126, v120, v121
	v_cvt_pk_bf16_f32 v127, v122, v123
	global_store_dwordx4 v144, v[124:127], s[14:15]
	s_waitcnt vmcnt(15)
; DI unsigned pk2(float a, float b) { f32x2 v = {a, b}; bf16x2_t r = __builtin_convertvector(v, bf16x2_t); return __builtin_bit_cast(unsigned, r); }
; DI float bflo(unsigned u) { return __uint_as_float(u << 16); }
; DI float bfhi(unsigned u) { return __uint_as_float(u & 0xffff0000u); }
;     DI void operator()(const f32x4 (&acc)[2][2][4][2], const Unit& u, int wr, int wc, int fr, int fq) const {
;     ...
; #pragma unroll
;         for (int ai = 0; ai < 2; ++ai)
; #pragma unroll
;             for (int m = 0; m < 4; ++m) { const size_t ro = (size_t)(row0 + ai * HALF + m * 16) * DM + col0;
; #pragma unroll
;                 for (int bj = 0; bj < 2; ++bj) {
;                     const u32x4 q = *(const u32x4*)(xb + ro + bj * HALF);
;                     const f32x4 b0 = {bflo(q.x), bfhi(q.x), bflo(q.y), bfhi(q.y)}, b1 = {bflo(q.z), bfhi(q.z), bflo(q.w), bfhi(q.w)};
;                     const f32x4 x0 = b0 + gv[bj][0] * acc[ai][bj][m][0], x1 = b1 + gv[bj][1] * acc[ai][bj][m][1];
;                     u32x4 w; w.x = pk2(x0.x, x0.y); w.y = pk2(x0.z, x0.w); w.z = pk2(x1.x, x1.y); w.w = pk2(x1.z, x1.w);
;                     *(u32x4*)(xb + ro + bj * HALF) = w; } }
	v_lshlrev_b32_e32 v248, 16, v188
	v_and_b32_e32 v249, 0xffff0000, v188
	v_lshlrev_b32_e32 v250, 16, v189
	v_and_b32_e32 v251, 0xffff0000, v189
	v_lshlrev_b32_e32 v252, 16, v190
	v_and_b32_e32 v253, 0xffff0000, v190
	v_lshlrev_b32_e32 v254, 16, v191
	v_and_b32_e32 v255, 0xffff0000, v191
	v_pk_fma_f32 v[112:113], v[112:113], v[136:137], v[248:249]
	v_pk_fma_f32 v[114:115], v[114:115], v[138:139], v[250:251]
	v_pk_fma_f32 v[104:105], v[104:105], v[140:141], v[252:253]
	v_pk_fma_f32 v[106:107], v[106:107], v[142:143], v[254:255]
	v_cvt_pk_bf16_f32 v112, v112, v113
	v_cvt_pk_bf16_f32 v113, v114, v115
	v_cvt_pk_bf16_f32 v114, v104, v105
	v_cvt_pk_bf16_f32 v115, v106, v107
	global_store_dwordx4 v144, v[112:115], s[14:15] offset:256
	s_waitcnt vmcnt(15)
	v_lshlrev_b32_e32 v248, 16, v192
	v_and_b32_e32 v249, 0xffff0000, v192
	v_lshlrev_b32_e32 v250, 16, v193
	v_and_b32_e32 v251, 0xffff0000, v193
	v_lshlrev_b32_e32 v252, 16, v194
	v_and_b32_e32 v253, 0xffff0000, v194
	v_lshlrev_b32_e32 v254, 16, v195
	v_and_b32_e32 v255, 0xffff0000, v195
	v_pk_fma_f32 v[116:117], v[116:117], v[128:129], v[248:249]
	v_pk_fma_f32 v[118:119], v[118:119], v[130:131], v[250:251]
	v_pk_fma_f32 v[108:109], v[108:109], v[132:133], v[252:253]
	v_pk_fma_f32 v[110:111], v[110:111], v[134:135], v[254:255]
	v_cvt_pk_bf16_f32 v116, v116, v117
	v_cvt_pk_bf16_f32 v117, v118, v119
	v_cvt_pk_bf16_f32 v118, v108, v109
	v_cvt_pk_bf16_f32 v119, v110, v111
	v_add_u32_e32 v146, 0x8000, v144
	global_store_dwordx4 v146, v[116:119], s[14:15]
	s_waitcnt vmcnt(15)
	v_lshlrev_b32_e32 v248, 16, v196
	v_and_b32_e32 v249, 0xffff0000, v196
	v_lshlrev_b32_e32 v250, 16, v197
	v_and_b32_e32 v251, 0xffff0000, v197
	v_lshlrev_b32_e32 v252, 16, v198
	v_and_b32_e32 v253, 0xffff0000, v198
	v_lshlrev_b32_e32 v254, 16, v199
	v_and_b32_e32 v255, 0xffff0000, v199
	v_pk_fma_f32 v[100:101], v[100:101], v[136:137], v[248:249]
	v_pk_fma_f32 v[102:103], v[102:103], v[138:139], v[250:251]
	v_pk_fma_f32 v[96:97], v[96:97], v[140:141], v[252:253]
	v_pk_fma_f32 v[98:99], v[98:99], v[142:143], v[254:255]
	v_cvt_pk_bf16_f32 v100, v100, v101
	v_cvt_pk_bf16_f32 v101, v102, v103
	v_cvt_pk_bf16_f32 v102, v96, v97
	v_cvt_pk_bf16_f32 v103, v98, v99
	v_add_u32_e32 v146, 0x8000, v144
	global_store_dwordx4 v146, v[100:103], s[14:15] offset:256
	s_waitcnt vmcnt(15)
	v_lshlrev_b32_e32 v248, 16, v200
	v_and_b32_e32 v249, 0xffff0000, v200
	v_lshlrev_b32_e32 v250, 16, v201
	v_and_b32_e32 v251, 0xffff0000, v201
	v_lshlrev_b32_e32 v252, 16, v202
	v_and_b32_e32 v253, 0xffff0000, v202
	v_lshlrev_b32_e32 v254, 16, v203
	v_and_b32_e32 v255, 0xffff0000, v203
	v_pk_fma_f32 v[92:93], v[92:93], v[128:129], v[248:249]
	v_pk_fma_f32 v[94:95], v[94:95], v[130:131], v[250:251]
	v_pk_fma_f32 v[88:89], v[88:89], v[132:133], v[252:253]
	v_pk_fma_f32 v[90:91], v[90:91], v[134:135], v[254:255]
	v_cvt_pk_bf16_f32 v92, v92, v93
	v_cvt_pk_bf16_f32 v93, v94, v95
	v_cvt_pk_bf16_f32 v94, v88, v89
	v_cvt_pk_bf16_f32 v95, v90, v91
	v_add_u32_e32 v146, 0x10000, v144
	global_store_dwordx4 v146, v[92:95], s[14:15]
	s_waitcnt vmcnt(15)
	v_lshlrev_b32_e32 v248, 16, v204
	v_and_b32_e32 v249, 0xffff0000, v204
	v_lshlrev_b32_e32 v250, 16, v205
	v_and_b32_e32 v251, 0xffff0000, v205
	v_lshlrev_b32_e32 v252, 16, v206
	v_and_b32_e32 v253, 0xffff0000, v206
	v_lshlrev_b32_e32 v254, 16, v207
	v_and_b32_e32 v255, 0xffff0000, v207
	v_pk_fma_f32 v[84:85], v[84:85], v[136:137], v[248:249]
	v_pk_fma_f32 v[86:87], v[86:87], v[138:139], v[250:251]
	v_pk_fma_f32 v[80:81], v[80:81], v[140:141], v[252:253]
	v_pk_fma_f32 v[82:83], v[82:83], v[142:143], v[254:255]
	v_cvt_pk_bf16_f32 v84, v84, v85
	v_cvt_pk_bf16_f32 v85, v86, v87
	v_cvt_pk_bf16_f32 v86, v80, v81
	v_cvt_pk_bf16_f32 v87, v82, v83
	v_add_u32_e32 v146, 0x10000, v144
	global_store_dwordx4 v146, v[84:87], s[14:15] offset:256
	s_waitcnt vmcnt(15)
	v_lshlrev_b32_e32 v248, 16, v208
	v_and_b32_e32 v249, 0xffff0000, v208
	v_lshlrev_b32_e32 v250, 16, v209
	v_and_b32_e32 v251, 0xffff0000, v209
	v_lshlrev_b32_e32 v252, 16, v210
	v_and_b32_e32 v253, 0xffff0000, v210
	v_lshlrev_b32_e32 v254, 16, v211
	v_and_b32_e32 v255, 0xffff0000, v211
	v_pk_fma_f32 v[76:77], v[76:77], v[128:129], v[248:249]
	v_pk_fma_f32 v[78:79], v[78:79], v[130:131], v[250:251]
	v_pk_fma_f32 v[72:73], v[72:73], v[132:133], v[252:253]
	v_pk_fma_f32 v[74:75], v[74:75], v[134:135], v[254:255]
	v_cvt_pk_bf16_f32 v76, v76, v77
	v_cvt_pk_bf16_f32 v77, v78, v79
	v_cvt_pk_bf16_f32 v78, v72, v73
	v_cvt_pk_bf16_f32 v79, v74, v75
	v_add_u32_e32 v146, 0x18000, v144
	global_store_dwordx4 v146, v[76:79], s[14:15]
	s_waitcnt vmcnt(15)
	v_lshlrev_b32_e32 v248, 16, v212
	v_and_b32_e32 v249, 0xffff0000, v212
	v_lshlrev_b32_e32 v250, 16, v213
	v_and_b32_e32 v251, 0xffff0000, v213
	v_lshlrev_b32_e32 v252, 16, v214
	v_and_b32_e32 v253, 0xffff0000, v214
	v_lshlrev_b32_e32 v254, 16, v215
	v_and_b32_e32 v255, 0xffff0000, v215
	v_pk_fma_f32 v[68:69], v[68:69], v[136:137], v[248:249]
	v_pk_fma_f32 v[70:71], v[70:71], v[138:139], v[250:251]
	v_pk_fma_f32 v[64:65], v[64:65], v[140:141], v[252:253]
	v_pk_fma_f32 v[66:67], v[66:67], v[142:143], v[254:255]
	v_cvt_pk_bf16_f32 v68, v68, v69
	v_cvt_pk_bf16_f32 v69, v70, v71
	v_cvt_pk_bf16_f32 v70, v64, v65
	v_cvt_pk_bf16_f32 v71, v66, v67
	v_add_u32_e32 v146, 0x18000, v144
	global_store_dwordx4 v146, v[68:71], s[14:15] offset:256
	s_waitcnt vmcnt(15)
; DI unsigned pk2(float a, float b) { f32x2 v = {a, b}; bf16x2_t r = __builtin_convertvector(v, bf16x2_t); return __builtin_bit_cast(unsigned, r); }
; DI float bflo(unsigned u) { return __uint_as_float(u << 16); }
; DI float bfhi(unsigned u) { return __uint_as_float(u & 0xffff0000u); }
;     DI void operator()(const f32x4 (&acc)[2][2][4][2], const Unit& u, int wr, int wc, int fr, int fq) const {
;     ...
; #pragma unroll
;         for (int ai = 0; ai < 2; ++ai)
; #pragma unroll
;             for (int m = 0; m < 4; ++m) { const size_t ro = (size_t)(row0 + ai * HALF + m * 16) * DM + col0;
; #pragma unroll
;                 for (int bj = 0; bj < 2; ++bj) {
;                     const u32x4 q = *(const u32x4*)(xb + ro + bj * HALF);
;                     const f32x4 b0 = {bflo(q.x), bfhi(q.x), bflo(q.y), bfhi(q.y)}, b1 = {bflo(q.z), bfhi(q.z), bflo(q.w), bfhi(q.w)};
;                     const f32x4 x0 = b0 + gv[bj][0] * acc[ai][bj][m][0], x1 = b1 + gv[bj][1] * acc[ai][bj][m][1];
;                     u32x4 w; w.x = pk2(x0.x, x0.y); w.y = pk2(x0.z, x0.w); w.z = pk2(x1.x, x1.y); w.w = pk2(x1.z, x1.w);
;                     *(u32x4*)(xb + ro + bj * HALF) = w; } }
	v_lshlrev_b32_e32 v248, 16, v216
	v_and_b32_e32 v249, 0xffff0000, v216
	v_lshlrev_b32_e32 v250, 16, v217
	v_and_b32_e32 v251, 0xffff0000, v217
	v_lshlrev_b32_e32 v252, 16, v218
	v_and_b32_e32 v253, 0xffff0000, v218
	v_lshlrev_b32_e32 v254, 16, v219
	v_and_b32_e32 v255, 0xffff0000, v219
	v_pk_fma_f32 v[60:61], v[60:61], v[128:129], v[248:249]
	v_pk_fma_f32 v[62:63], v[62:63], v[130:131], v[250:251]
	v_pk_fma_f32 v[56:57], v[56:57], v[132:133], v[252:253]
	v_pk_fma_f32 v[58:59], v[58:59], v[134:135], v[254:255]
	v_cvt_pk_bf16_f32 v60, v60, v61
	v_cvt_pk_bf16_f32 v61, v62, v63
	v_cvt_pk_bf16_f32 v62, v56, v57
	v_cvt_pk_bf16_f32 v63, v58, v59
	v_add_u32_e32 v146, 0x40000, v144
	global_store_dwordx4 v146, v[60:63], s[14:15]
	s_waitcnt vmcnt(15)
	v_lshlrev_b32_e32 v248, 16, v220
	v_and_b32_e32 v249, 0xffff0000, v220
	v_lshlrev_b32_e32 v250, 16, v221
	v_and_b32_e32 v251, 0xffff0000, v221
	v_lshlrev_b32_e32 v252, 16, v222
	v_and_b32_e32 v253, 0xffff0000, v222
	v_lshlrev_b32_e32 v254, 16, v223
	v_and_b32_e32 v255, 0xffff0000, v223
	v_pk_fma_f32 v[52:53], v[52:53], v[136:137], v[248:249]
	v_pk_fma_f32 v[54:55], v[54:55], v[138:139], v[250:251]
	v_pk_fma_f32 v[48:49], v[48:49], v[140:141], v[252:253]
	v_pk_fma_f32 v[50:51], v[50:51], v[142:143], v[254:255]
	v_cvt_pk_bf16_f32 v52, v52, v53
	v_cvt_pk_bf16_f32 v53, v54, v55
	v_cvt_pk_bf16_f32 v54, v48, v49
	v_cvt_pk_bf16_f32 v55, v50, v51
	v_add_u32_e32 v146, 0x40000, v144
	global_store_dwordx4 v146, v[52:55], s[14:15] offset:256
	s_waitcnt vmcnt(15)
	v_lshlrev_b32_e32 v248, 16, v224
	v_and_b32_e32 v249, 0xffff0000, v224
	v_lshlrev_b32_e32 v250, 16, v225
	v_and_b32_e32 v251, 0xffff0000, v225
	v_lshlrev_b32_e32 v252, 16, v226
	v_and_b32_e32 v253, 0xffff0000, v226
	v_lshlrev_b32_e32 v254, 16, v227
	v_and_b32_e32 v255, 0xffff0000, v227
	v_pk_fma_f32 v[44:45], v[44:45], v[128:129], v[248:249]
	v_pk_fma_f32 v[46:47], v[46:47], v[130:131], v[250:251]
	v_pk_fma_f32 v[40:41], v[40:41], v[132:133], v[252:253]
	v_pk_fma_f32 v[42:43], v[42:43], v[134:135], v[254:255]
	v_cvt_pk_bf16_f32 v44, v44, v45
	v_cvt_pk_bf16_f32 v45, v46, v47
	v_cvt_pk_bf16_f32 v46, v40, v41
	v_cvt_pk_bf16_f32 v47, v42, v43
	v_add_u32_e32 v146, 0x48000, v144
	global_store_dwordx4 v146, v[44:47], s[14:15]
	s_waitcnt vmcnt(15)
	v_lshlrev_b32_e32 v248, 16, v228
	v_and_b32_e32 v249, 0xffff0000, v228
	v_lshlrev_b32_e32 v250, 16, v229
	v_and_b32_e32 v251, 0xffff0000, v229
	v_lshlrev_b32_e32 v252, 16, v230
	v_and_b32_e32 v253, 0xffff0000, v230
	v_lshlrev_b32_e32 v254, 16, v231
	v_and_b32_e32 v255, 0xffff0000, v231
	v_pk_fma_f32 v[28:29], v[28:29], v[136:137], v[248:249]
	v_pk_fma_f32 v[30:31], v[30:31], v[138:139], v[250:251]
	v_pk_fma_f32 v[24:25], v[24:25], v[140:141], v[252:253]
	v_pk_fma_f32 v[26:27], v[26:27], v[142:143], v[254:255]
	v_cvt_pk_bf16_f32 v28, v28, v29
	v_cvt_pk_bf16_f32 v29, v30, v31
	v_cvt_pk_bf16_f32 v30, v24, v25
	v_cvt_pk_bf16_f32 v31, v26, v27
	v_add_u32_e32 v146, 0x48000, v144
	global_store_dwordx4 v146, v[28:31], s[14:15] offset:256
	s_waitcnt vmcnt(15)
	v_lshlrev_b32_e32 v248, 16, v232
	v_and_b32_e32 v249, 0xffff0000, v232
	v_lshlrev_b32_e32 v250, 16, v233
	v_and_b32_e32 v251, 0xffff0000, v233
	v_lshlrev_b32_e32 v252, 16, v234
	v_and_b32_e32 v253, 0xffff0000, v234
	v_lshlrev_b32_e32 v254, 16, v235
	v_and_b32_e32 v255, 0xffff0000, v235
	v_pk_fma_f32 v[36:37], v[36:37], v[128:129], v[248:249]
	v_pk_fma_f32 v[38:39], v[38:39], v[130:131], v[250:251]
	v_pk_fma_f32 v[32:33], v[32:33], v[132:133], v[252:253]
	v_pk_fma_f32 v[34:35], v[34:35], v[134:135], v[254:255]
	v_cvt_pk_bf16_f32 v36, v36, v37
	v_cvt_pk_bf16_f32 v37, v38, v39
	v_cvt_pk_bf16_f32 v38, v32, v33
	v_cvt_pk_bf16_f32 v39, v34, v35
	v_add_u32_e32 v146, 0x50000, v144
	global_store_dwordx4 v146, v[36:39], s[14:15]
	s_waitcnt vmcnt(15)
	v_lshlrev_b32_e32 v248, 16, v236
	v_and_b32_e32 v249, 0xffff0000, v236
	v_lshlrev_b32_e32 v250, 16, v237
	v_and_b32_e32 v251, 0xffff0000, v237
	v_lshlrev_b32_e32 v252, 16, v238
	v_and_b32_e32 v253, 0xffff0000, v238
	v_lshlrev_b32_e32 v254, 16, v239
	v_and_b32_e32 v255, 0xffff0000, v239
	v_pk_fma_f32 v[12:13], v[12:13], v[136:137], v[248:249]
	v_pk_fma_f32 v[14:15], v[14:15], v[138:139], v[250:251]
	v_pk_fma_f32 v[8:9], v[8:9], v[140:141], v[252:253]
	v_pk_fma_f32 v[10:11], v[10:11], v[142:143], v[254:255]
	v_cvt_pk_bf16_f32 v12, v12, v13
	v_cvt_pk_bf16_f32 v13, v14, v15
	v_cvt_pk_bf16_f32 v14, v8, v9
	v_cvt_pk_bf16_f32 v15, v10, v11
	v_add_u32_e32 v146, 0x50000, v144
	global_store_dwordx4 v146, v[12:15], s[14:15] offset:256
	s_waitcnt vmcnt(15)
	v_lshlrev_b32_e32 v248, 16, v240
	v_and_b32_e32 v249, 0xffff0000, v240
	v_lshlrev_b32_e32 v250, 16, v241
	v_and_b32_e32 v251, 0xffff0000, v241
	v_lshlrev_b32_e32 v252, 16, v242
	v_and_b32_e32 v253, 0xffff0000, v242
	v_lshlrev_b32_e32 v254, 16, v243
	v_and_b32_e32 v255, 0xffff0000, v243
	v_pk_fma_f32 v[20:21], v[20:21], v[128:129], v[248:249]
	v_pk_fma_f32 v[22:23], v[22:23], v[130:131], v[250:251]
	v_pk_fma_f32 v[16:17], v[16:17], v[132:133], v[252:253]
	v_pk_fma_f32 v[18:19], v[18:19], v[134:135], v[254:255]
	v_cvt_pk_bf16_f32 v20, v20, v21
	v_cvt_pk_bf16_f32 v21, v22, v23
	v_cvt_pk_bf16_f32 v22, v16, v17
	v_cvt_pk_bf16_f32 v23, v18, v19
	v_add_u32_e32 v146, 0x58000, v144
	global_store_dwordx4 v146, v[20:23], s[14:15]
	s_waitcnt vmcnt(15)
	v_lshlrev_b32_e32 v248, 16, v244
	v_and_b32_e32 v249, 0xffff0000, v244
	v_lshlrev_b32_e32 v250, 16, v245
	v_and_b32_e32 v251, 0xffff0000, v245
	v_lshlrev_b32_e32 v252, 16, v246
	v_and_b32_e32 v253, 0xffff0000, v246
	v_lshlrev_b32_e32 v254, 16, v247
	v_and_b32_e32 v255, 0xffff0000, v247
	v_pk_fma_f32 v[4:5], v[4:5], v[136:137], v[248:249]
	v_pk_fma_f32 v[6:7], v[6:7], v[138:139], v[250:251]
	v_pk_fma_f32 v[0:1], v[0:1], v[140:141], v[252:253]
	v_pk_fma_f32 v[2:3], v[2:3], v[142:143], v[254:255]
	v_cvt_pk_bf16_f32 v4, v4, v5
	v_cvt_pk_bf16_f32 v5, v6, v7
	v_cvt_pk_bf16_f32 v6, v0, v1
	v_cvt_pk_bf16_f32 v7, v2, v3
	v_add_u32_e32 v146, 0x58000, v144
	global_store_dwordx4 v146, v[4:7], s[14:15] offset:256
	s_and_b64 vcc, exec, s[4:5]
	s_cbranch_vccz .LBB0_917
	s_waitcnt vmcnt(0)
	s_cmpk_gt_u32 s42, 0xff
	s_cbranch_scc1 .LBB0_932
	s_barrier

; __global__ void __launch_bounds__(512, 2) mega(Params p) {
;     extern __shared__ __attribute__((aligned(16))) unsigned char smem[];
	.amdhsa_kernel _Z4mega6Params
		.amdhsa_group_segment_fixed_size 0
		.amdhsa_private_segment_fixed_size 0
		.amdhsa_kernarg_size 440
		.amdhsa_user_sgpr_count 2
		.amdhsa_user_sgpr_dispatch_ptr 0
		.amdhsa_user_sgpr_queue_ptr 0
		.amdhsa_user_sgpr_kernarg_segment_ptr 1
		.amdhsa_user_sgpr_dispatch_id 0
		.amdhsa_user_sgpr_kernarg_preload_length 0
		.amdhsa_user_sgpr_kernarg_preload_offset 0
		.amdhsa_user_sgpr_private_segment_size 0
		.amdhsa_uses_dynamic_stack 0
		.amdhsa_enable_private_segment 0
		.amdhsa_system_sgpr_workgroup_id_x 1
		.amdhsa_system_sgpr_workgroup_id_y 0
		.amdhsa_system_sgpr_workgroup_id_z 0
		.amdhsa_system_sgpr_workgroup_info 0
		.amdhsa_system_vgpr_workitem_id 2
		.amdhsa_next_free_vgpr 256
		.amdhsa_next_free_sgpr 88
		.amdhsa_accum_offset 256
		.amdhsa_reserve_vcc 1
		.amdhsa_float_round_mode_32 0
		.amdhsa_float_round_mode_16_64 0
		.amdhsa_float_denorm_mode_32 3
		.amdhsa_float_denorm_mode_16_64 3
		.amdhsa_dx10_clamp 1
		.amdhsa_ieee_mode 1
		.amdhsa_fp16_overflow 0
		.amdhsa_tg_split 0
		.amdhsa_exception_fp_ieee_invalid_op 0
		.amdhsa_exception_fp_denorm_src 0
		.amdhsa_exception_fp_ieee_div_zero 0
		.amdhsa_exception_fp_ieee_overflow 0
		.amdhsa_exception_fp_ieee_underflow 0
		.amdhsa_exception_fp_ieee_inexact 0
		.amdhsa_exception_int_div_zero 0
	.end_amdhsa_kernel

; __global__ void __launch_bounds__(512, 2) mega(Params p) {
;     extern __shared__ __attribute__((aligned(16))) unsigned char smem[];
amdhsa.kernels:
  - .agpr_count:     0
    .args:
      - .offset:         0
        .size:           184
        .value_kind:     by_value
      - .offset:         184
        .size:           4
        .value_kind:     hidden_block_count_x
      - .offset:         188
        .size:           4
        .value_kind:     hidden_block_count_y
      - .offset:         192
        .size:           4
        .value_kind:     hidden_block_count_z
      - .offset:         196
        .size:           2
        .value_kind:     hidden_group_size_x
      - .offset:         198
        .size:           2
        .value_kind:     hidden_group_size_y
      - .offset:         200
        .size:           2
        .value_kind:     hidden_group_size_z
      - .offset:         202
        .size:           2
        .value_kind:     hidden_remainder_x
      - .offset:         204
        .size:           2
        .value_kind:     hidden_remainder_y
      - .offset:         206
        .size:           2
        .value_kind:     hidden_remainder_z
      - .offset:         224
        .size:           8
        .value_kind:     hidden_global_offset_x
      - .offset:         232
        .size:           8
        .value_kind:     hidden_global_offset_y
      - .offset:         240
        .size:           8
        .value_kind:     hidden_global_offset_z
      - .offset:         248
        .size:           2
        .value_kind:     hidden_grid_dims
      - .offset:         272
        .size:           8
        .value_kind:     hidden_multigrid_sync_arg
      - .offset:         304
        .size:           4
        .value_kind:     hidden_dynamic_lds_size
    .group_segment_fixed_size: 0
    .kernarg_segment_align: 8
    .kernarg_segment_size: 440
    .language:       OpenCL C
    .language_version:
      - 2
      - 0
    .max_flat_workgroup_size: 512
    .name:           _Z4mega6Params
    .private_segment_fixed_size: 0
    .sgpr_count:     94
    .sgpr_spill_count: 0
    .symbol:         _Z4mega6Params.kd
    .uniform_work_group_size: 1
    .uses_dynamic_stack: false
    .vgpr_count:     256
    .vgpr_spill_count: 0
    .wavefront_size: 64
